# baseline (speedup 1.0000x reference)
.LBB0_358:
	s_or_b64 exec, exec, s[2:3]
	v_mov_b32_e32 v200, v180
	s_waitcnt lgkmcnt(0)
	s_barrier
	s_nop 0
	v_cmp_gt_i32_e32 vcc, s56, v200
	s_and_saveexec_b64 s[2:3], vcc
	s_cbranch_execz .LBB0_360
	v_ashrrev_i32_e32 v181, 31, v200
	v_add_u32_sdwa v181, v200, v181 dst_sel:DWORD dst_unused:UNUSED_PAD src0_sel:DWORD src1_sel:BYTE_3
	v_ashrrev_i32_e32 v181, 8, v181
	v_mul_i32_i24_e32 v201, 0x100, v181
	v_sub_u32_e32 v200, v200, v201
	v_ashrrev_i16_e32 v201, 15, v200
	v_lshrrev_b16_e32 v201, 12, v201
	v_add_u16_e32 v201, v200, v201
	v_ashrrev_i16_e32 v233, 4, v201
	v_and_b32_e32 v201, -16, v201
	v_mul_i32_i24_e32 v181, 0x1100, v181
	v_sub_u16_e32 v204, v200, v201
	v_lshlrev_b32_e32 v234, 3, v181
	v_lshlrev_b32_e32 v201, 3, v200
	v_ashrrev_i32_e32 v200, 4, v200
	v_add_u32_e32 v181, s57, v234
	v_lshlrev_b32_e32 v200, 3, v200
	v_add3_u32 v181, v181, v201, v200
	v_bfe_i32 v235, v204, 0, 16
	ds_read_b64 v[200:201], v181
	ds_read_b64 v[202:203], v181 offset:2176
	ds_read_b64 v[214:215], v181 offset:4352
	ds_read_b64 v[216:217], v181 offset:6528
	ds_read_b64 v[218:219], v181 offset:8704
	ds_read_b64 v[222:223], v181 offset:10880
	ds_read_b64 v[224:225], v181 offset:13056
	ds_read_b64 v[226:227], v181 offset:15232
	ds_read_b64 v[228:229], v181 offset:17408
	ds_read_b64 v[230:231], v181 offset:19584
	ds_read_b64 v[236:237], v181 offset:21760
	ds_read_b64 v[238:239], v181 offset:23936
	ds_read_b64 v[242:243], v181 offset:26112
	ds_read_b64 v[244:245], v181 offset:28288
	ds_read_b64 v[246:247], v181 offset:30464
	ds_read_b64 v[206:207], v181 offset:32640
	v_mad_i32_i24 v181, v235, s27, 0
	v_add_u32_e32 v204, 0x808, v181
	ds_read2_b64 v[210:213], v204 offset1:1
	s_mov_b32 s61, s34
	s_mov_b32 s35, s24
	s_waitcnt lgkmcnt(0)
	v_pk_mul_f32 v[204:205], v[202:203], v[210:211] op_sel:[1,1] op_sel_hi:[1,0]
	s_nop 0
	v_pk_fma_f32 v[208:209], v[202:203], v[210:211], v[204:205] op_sel_hi:[0,1,1] neg_lo:[0,0,1]
	v_pk_mul_f32 v[202:203], v[214:215], v[212:213] op_sel:[1,1] op_sel_hi:[1,0]
	s_nop 0
	v_pk_fma_f32 v[204:205], v[214:215], v[212:213], v[202:203] op_sel_hi:[0,1,1] neg_lo:[0,0,1]
	v_add_u32_e32 v202, 0x818, v181
	ds_read2_b64 v[210:213], v202 offset1:1
	s_waitcnt lgkmcnt(0)
	v_pk_mul_f32 v[214:215], v[216:217], v[210:211] op_sel:[1,1] op_sel_hi:[1,0]
	s_nop 0
	v_pk_fma_f32 v[202:203], v[216:217], v[210:211], v[214:215] op_sel_hi:[0,1,1] neg_lo:[0,0,1]
	v_pk_mul_f32 v[210:211], v[218:219], v[212:213] op_sel:[1,1] op_sel_hi:[1,0]
	s_nop 0
	v_pk_fma_f32 v[216:217], v[218:219], v[212:213], v[210:211] op_sel_hi:[0,1,1] neg_lo:[0,0,1]
	v_add_u32_e32 v210, 0x828, v181
	ds_read2_b64 v[218:221], v210 offset1:1
	s_waitcnt lgkmcnt(0)
	v_pk_mul_f32 v[210:211], v[222:223], v[218:219] op_sel:[1,1] op_sel_hi:[1,0]
	s_nop 0
	v_pk_fma_f32 v[214:215], v[222:223], v[218:219], v[210:211] op_sel_hi:[0,1,1] neg_lo:[0,0,1]
	v_pk_mul_f32 v[210:211], v[224:225], v[220:221] op_sel:[1,1] op_sel_hi:[1,0]
	s_nop 0
	v_pk_fma_f32 v[212:213], v[224:225], v[220:221], v[210:211] op_sel_hi:[0,1,1] neg_lo:[0,0,1]
	v_add_u32_e32 v210, 0x838, v181
	ds_read2_b64 v[218:221], v210 offset1:1
	s_waitcnt lgkmcnt(0)
	v_pk_mul_f32 v[222:223], v[226:227], v[218:219] op_sel:[1,1] op_sel_hi:[1,0]
	s_nop 0
	v_pk_fma_f32 v[210:211], v[226:227], v[218:219], v[222:223] op_sel_hi:[0,1,1] neg_lo:[0,0,1]
	v_pk_mul_f32 v[218:219], v[228:229], v[220:221] op_sel:[1,1] op_sel_hi:[1,0]
	s_nop 0
	v_pk_fma_f32 v[224:225], v[228:229], v[220:221], v[218:219] op_sel_hi:[0,1,1] neg_lo:[0,0,1]
	v_add_u32_e32 v218, 0x848, v181
	ds_read2_b64 v[226:229], v218 offset1:1
	s_waitcnt lgkmcnt(0)
	v_pk_mul_f32 v[218:219], v[230:231], v[226:227] op_sel:[1,1] op_sel_hi:[1,0]
	s_nop 0
	v_pk_fma_f32 v[222:223], v[230:231], v[226:227], v[218:219] op_sel_hi:[0,1,1] neg_lo:[0,0,1]
	v_pk_mul_f32 v[218:219], v[236:237], v[228:229] op_sel:[1,1] op_sel_hi:[1,0]
	s_nop 0
	v_pk_fma_f32 v[220:221], v[236:237], v[228:229], v[218:219] op_sel_hi:[0,1,1] neg_lo:[0,0,1]
	v_add_u32_e32 v218, 0x858, v181
	ds_read2_b64 v[226:229], v218 offset1:1
	s_waitcnt lgkmcnt(0)
	v_pk_mul_f32 v[230:231], v[238:239], v[226:227] op_sel:[1,1] op_sel_hi:[1,0]
	s_nop 0
	v_pk_fma_f32 v[218:219], v[238:239], v[226:227], v[230:231] op_sel_hi:[0,1,1] neg_lo:[0,0,1]
	v_pk_mul_f32 v[226:227], v[242:243], v[228:229] op_sel:[1,1] op_sel_hi:[1,0]
	s_nop 0
	v_pk_fma_f32 v[230:231], v[242:243], v[228:229], v[226:227] op_sel_hi:[0,1,1] neg_lo:[0,0,1]
	v_add_u32_e32 v226, 0x868, v181
	ds_read2_b64 v[236:239], v226 offset1:1
	s_waitcnt lgkmcnt(0)
	v_pk_mul_f32 v[226:227], v[244:245], v[236:237] op_sel:[1,1] op_sel_hi:[1,0]
	s_nop 0
	v_pk_fma_f32 v[228:229], v[244:245], v[236:237], v[226:227] op_sel_hi:[0,1,1] neg_lo:[0,0,1]
	v_pk_mul_f32 v[236:237], v[246:247], v[238:239] op_sel:[1,1] op_sel_hi:[1,0]
	v_pk_fma_f32 v[226:227], v[246:247], v[238:239], v[236:237] op_sel_hi:[0,1,1] neg_lo:[0,0,1]
	ds_read_b64 v[236:237], v181 offset:2168
	v_bfe_i32 v181, v233, 0, 16
	v_lshl_add_u32 v181, v181, 8, v235
	s_waitcnt lgkmcnt(0)
	v_pk_mul_f32 v[238:239], v[206:207], v[236:237] op_sel:[1,1] op_sel_hi:[1,0]
	s_nop 0
	v_pk_fma_f32 v[242:243], v[206:207], v[236:237], v[238:239] op_sel_hi:[0,1,1] neg_lo:[0,0,1]
	v_pk_add_f32 v[206:207], v[200:201], v[224:225]
	v_pk_add_f32 v[200:201], v[200:201], v[224:225] neg_lo:[0,1] neg_hi:[0,1]
	v_pk_add_f32 v[224:225], v[216:217], v[230:231]
	v_pk_add_f32 v[216:217], v[216:217], v[230:231] neg_lo:[0,1] neg_hi:[0,1]
	s_nop 0
	v_xor_b32_e32 v231, 0x80000000, v216
	v_mov_b32_e32 v230, v217
	v_pk_add_f32 v[216:217], v[206:207], v[224:225]
	v_pk_add_f32 v[206:207], v[206:207], v[224:225] neg_lo:[0,1] neg_hi:[0,1]
	v_pk_add_f32 v[224:225], v[208:209], v[222:223]
	v_pk_add_f32 v[208:209], v[208:209], v[222:223] neg_lo:[0,1] neg_hi:[0,1]
	v_pk_add_f32 v[222:223], v[214:215], v[228:229]
	v_pk_add_f32 v[214:215], v[214:215], v[228:229] neg_lo:[0,1] neg_hi:[0,1]
	v_pk_add_f32 v[236:237], v[200:201], v[230:231]
	v_xor_b32_e32 v229, 0x80000000, v214
	v_mov_b32_e32 v228, v215
	v_pk_add_f32 v[214:215], v[224:225], v[222:223]
	v_pk_add_f32 v[222:223], v[224:225], v[222:223] neg_lo:[0,1] neg_hi:[0,1]
	v_pk_add_f32 v[224:225], v[204:205], v[220:221]
	v_pk_add_f32 v[204:205], v[204:205], v[220:221] neg_lo:[0,1] neg_hi:[0,1]
	v_pk_add_f32 v[220:221], v[212:213], v[226:227]
	v_pk_add_f32 v[212:213], v[212:213], v[226:227] neg_lo:[0,1] neg_hi:[0,1]
	v_pk_add_f32 v[200:201], v[200:201], v[230:231] neg_lo:[0,1] neg_hi:[0,1]
	v_pk_add_f32 v[230:231], v[208:209], v[228:229]
	v_xor_b32_e32 v227, 0x80000000, v212
	v_mov_b32_e32 v226, v213
	v_pk_add_f32 v[212:213], v[224:225], v[220:221]
	v_pk_add_f32 v[220:221], v[224:225], v[220:221] neg_lo:[0,1] neg_hi:[0,1]
	v_pk_add_f32 v[224:225], v[202:203], v[218:219]
	v_pk_add_f32 v[202:203], v[202:203], v[218:219] neg_lo:[0,1] neg_hi:[0,1]
	v_pk_add_f32 v[218:219], v[210:211], v[242:243]
	v_pk_add_f32 v[210:211], v[210:211], v[242:243] neg_lo:[0,1] neg_hi:[0,1]
	v_pk_add_f32 v[208:209], v[208:209], v[228:229] neg_lo:[0,1] neg_hi:[0,1]
	v_pk_add_f32 v[228:229], v[204:205], v[226:227]
	v_pk_add_f32 v[204:205], v[204:205], v[226:227] neg_lo:[0,1] neg_hi:[0,1]
	v_xor_b32_e32 v227, 0x80000000, v210
	v_mov_b32_e32 v226, v211
	v_pk_add_f32 v[210:211], v[224:225], v[218:219]
	v_pk_add_f32 v[218:219], v[224:225], v[218:219] neg_lo:[0,1] neg_hi:[0,1]
	v_pk_mul_f32 v[224:225], v[230:231], s[24:25] op_sel_hi:[1,0]
	v_pk_add_f32 v[238:239], v[202:203], v[226:227]
	v_pk_add_f32 v[202:203], v[202:203], v[226:227] neg_lo:[0,1] neg_hi:[0,1]
	v_pk_fma_f32 v[226:227], v[230:231], s[26:27], v[224:225] op_sel:[0,0,1] op_sel_hi:[1,0,0] neg_hi:[0,0,1]
	s_nop 0
	v_pk_mul_f32 v[224:225], v[222:223], s[28:29] op_sel_hi:[1,0]
	s_nop 0
	v_pk_fma_f32 v[230:231], v[222:223], s[28:29], v[224:225] op_sel:[0,0,1] op_sel_hi:[1,0,0] neg_hi:[0,0,1]
	v_pk_mul_f32 v[224:225], v[208:209], s[26:27] op_sel_hi:[1,0]
	v_pk_fma_f32 v[242:243], v[208:209], s[24:25], v[224:225] op_sel:[0,0,1] op_sel_hi:[1,0,0] neg_hi:[0,0,1]
	s_nop 0
	v_pk_mul_f32 v[208:209], v[228:229], s[28:29] op_sel_hi:[1,0]
	s_nop 0
	v_pk_fma_f32 v[224:225], v[228:229], s[28:29], v[208:209] op_sel:[0,0,1] op_sel_hi:[1,0,0] neg_hi:[0,0,1]
	s_nop 0
	v_pk_fma_f32 v[208:209], v[220:221], 0, v[220:221] op_sel:[0,0,1] op_sel_hi:[1,0,0] neg_hi:[0,0,1]
	s_nop 0
	v_pk_mul_f32 v[220:221], v[204:205], s[30:31] op_sel_hi:[1,0]
	s_nop 0
	v_pk_fma_f32 v[228:229], v[204:205], s[30:31], v[220:221] op_sel:[0,0,1] op_sel_hi:[1,0,0] neg_lo:[0,0,1]
	v_pk_mul_f32 v[220:221], v[238:239], s[26:27] op_sel_hi:[1,0]
	v_pk_fma_f32 v[244:245], v[238:239], s[24:25], v[220:221] op_sel:[0,0,1] op_sel_hi:[1,0,0] neg_hi:[0,0,1]
	v_pk_add_f32 v[204:205], v[200:201], v[228:229]
	v_pk_mul_f32 v[220:221], v[218:219], s[30:31] op_sel_hi:[1,0]
	v_pk_add_f32 v[200:201], v[200:201], v[228:229] neg_lo:[0,1] neg_hi:[0,1]
	v_pk_fma_f32 v[238:239], v[218:219], s[30:31], v[220:221] op_sel:[0,0,1] op_sel_hi:[1,0,0] neg_lo:[0,0,1]
	s_nop 0
	v_pk_mul_f32 v[218:219], v[202:203], s[60:61] op_sel:[1,0]
	v_pk_add_f32 v[222:223], v[230:231], v[238:239] neg_lo:[0,1] neg_hi:[0,1]
	v_pk_fma_f32 v[202:203], v[202:203], s[34:35], v[218:219] op_sel_hi:[0,1,1]
	v_pk_add_f32 v[218:219], v[216:217], v[212:213]
	v_pk_add_f32 v[212:213], v[216:217], v[212:213] neg_lo:[0,1] neg_hi:[0,1]
	v_pk_add_f32 v[216:217], v[214:215], v[210:211]
	v_pk_add_f32 v[210:211], v[214:215], v[210:211] neg_lo:[0,1] neg_hi:[0,1]
	s_nop 0
	v_xor_b32_e32 v215, 0x80000000, v210
	v_mov_b32_e32 v214, v211
	v_pk_add_f32 v[210:211], v[218:219], v[216:217]
	v_pk_add_f32 v[220:221], v[212:213], v[214:215]
	v_pk_add_f32 v[216:217], v[218:219], v[216:217] neg_lo:[0,1] neg_hi:[0,1]
	v_pk_add_f32 v[212:213], v[212:213], v[214:215] neg_lo:[0,1] neg_hi:[0,1]
	v_pk_add_f32 v[214:215], v[236:237], v[224:225]
	v_pk_add_f32 v[218:219], v[236:237], v[224:225] neg_lo:[0,1] neg_hi:[0,1]
	v_pk_add_f32 v[224:225], v[226:227], v[244:245]
	v_pk_add_f32 v[226:227], v[226:227], v[244:245] neg_lo:[0,1] neg_hi:[0,1]
	s_nop 0
	v_xor_b32_e32 v237, 0x80000000, v226
	v_mov_b32_e32 v236, v227
	v_pk_add_f32 v[226:227], v[214:215], v[224:225]
	v_pk_add_f32 v[214:215], v[214:215], v[224:225] neg_lo:[0,1] neg_hi:[0,1]
	v_pk_add_f32 v[224:225], v[206:207], v[208:209]
	v_pk_add_f32 v[206:207], v[206:207], v[208:209] neg_lo:[0,1] neg_hi:[0,1]
	v_pk_add_f32 v[208:209], v[230:231], v[238:239]
	v_xor_b32_e32 v231, 0x80000000, v222
	v_mov_b32_e32 v230, v223
	v_pk_add_f32 v[222:223], v[224:225], v[208:209]
	v_pk_add_f32 v[208:209], v[224:225], v[208:209] neg_lo:[0,1] neg_hi:[0,1]
	v_pk_add_f32 v[224:225], v[242:243], v[202:203]
	v_pk_add_f32 v[202:203], v[242:243], v[202:203] neg_lo:[0,1] neg_hi:[0,1]
	v_pk_add_f32 v[244:245], v[218:219], v[236:237]
	v_xor_b32_e32 v229, 0x80000000, v202
	v_mov_b32_e32 v228, v203
	v_pk_add_f32 v[202:203], v[204:205], v[224:225]
	v_pk_add_f32 v[204:205], v[204:205], v[224:225] neg_lo:[0,1] neg_hi:[0,1]
	v_lshlrev_b32_e32 v225, 3, v181
	v_ashrrev_i32_e32 v181, 4, v181
	v_add_u32_e32 v224, 0, v234
	v_lshlrev_b32_e32 v181, 3, v181
	v_add3_u32 v181, v224, v225, v181
	v_pk_add_f32 v[218:219], v[218:219], v[236:237] neg_lo:[0,1] neg_hi:[0,1]
	v_pk_add_f32 v[236:237], v[206:207], v[230:231]
	v_pk_add_f32 v[206:207], v[206:207], v[230:231] neg_lo:[0,1] neg_hi:[0,1]
	v_pk_add_f32 v[230:231], v[200:201], v[228:229]
	v_pk_add_f32 v[200:201], v[200:201], v[228:229] neg_lo:[0,1] neg_hi:[0,1]
	v_add_u32_e32 v224, 0x1800, v181
	v_add_u32_e32 v181, 0x1c00, v181
	ds_write2_b64 v224, v[210:211], v[226:227] offset0:16 offset1:33
	ds_write2_b64 v224, v[222:223], v[202:203] offset0:50 offset1:67
	ds_write2_b64 v224, v[220:221], v[244:245] offset0:84 offset1:101
	ds_write2_b64 v224, v[236:237], v[230:231] offset0:118 offset1:135
	ds_write2_b64 v224, v[216:217], v[214:215] offset0:152 offset1:169
	ds_write2_b64 v224, v[208:209], v[204:205] offset0:186 offset1:203
	ds_write2_b64 v224, v[212:213], v[218:219] offset0:220 offset1:237
	ds_write2_b64 v181, v[206:207], v[200:201] offset0:126 offset1:143

.LBB0_364:
	s_or_b64 exec, exec, s[2:3]
	v_mov_b32_e32 v200, v180
	s_waitcnt lgkmcnt(0)
	s_barrier
	s_nop 0
	v_cmp_gt_i32_e32 vcc, s56, v200
	s_and_saveexec_b64 s[2:3], vcc
	s_cbranch_execz .LBB0_366
	v_ashrrev_i32_e32 v181, 31, v200
	v_add_u32_sdwa v181, v200, v181 dst_sel:DWORD dst_unused:UNUSED_PAD src0_sel:DWORD src1_sel:BYTE_3
	v_ashrrev_i32_e32 v181, 8, v181
	v_mul_i32_i24_e32 v201, 0x100, v181
	v_sub_u32_e32 v200, v200, v201
	v_ashrrev_i16_e32 v201, 15, v200
	v_lshrrev_b16_e32 v201, 12, v201
	v_add_u16_e32 v201, v200, v201
	v_ashrrev_i16_e32 v233, 4, v201
	v_and_b32_e32 v201, -16, v201
	v_mul_i32_i24_e32 v181, 0x1100, v181
	v_sub_u16_e32 v204, v200, v201
	v_lshlrev_b32_e32 v234, 3, v181
	v_lshlrev_b32_e32 v201, 3, v200
	v_ashrrev_i32_e32 v200, 4, v200
	v_add_u32_e32 v181, 0, v234
	v_lshlrev_b32_e32 v200, 3, v200
	v_add3_u32 v181, v181, v201, v200
	v_bfe_i32 v235, v204, 0, 16
	ds_read_b64 v[200:201], v181 offset:6272
	ds_read_b64 v[202:203], v181 offset:8448
	ds_read_b64 v[214:215], v181 offset:10624
	ds_read_b64 v[216:217], v181 offset:12800
	ds_read_b64 v[218:219], v181 offset:14976
	ds_read_b64 v[222:223], v181 offset:17152
	ds_read_b64 v[224:225], v181 offset:19328
	ds_read_b64 v[226:227], v181 offset:21504
	ds_read_b64 v[228:229], v181 offset:23680
	ds_read_b64 v[230:231], v181 offset:25856
	ds_read_b64 v[236:237], v181 offset:28032
	ds_read_b64 v[238:239], v181 offset:30208
	ds_read_b64 v[242:243], v181 offset:32384
	ds_read_b64 v[244:245], v181 offset:34560
	ds_read_b64 v[246:247], v181 offset:36736
	ds_read_b64 v[206:207], v181 offset:38912
	v_mad_i32_i24 v181, v235, s27, 0
	v_add_u32_e32 v204, 0x808, v181
	ds_read2_b64 v[210:213], v204 offset1:1
	s_mov_b32 s35, s60
	s_waitcnt lgkmcnt(0)
	v_pk_mul_f32 v[204:205], v[202:203], v[210:211] op_sel:[1,1] op_sel_hi:[0,1]
	v_pk_fma_f32 v[208:209], v[202:203], v[210:211], v[204:205]
	v_pk_fma_f32 v[202:203], v[202:203], v[210:211], v[204:205] op_sel_hi:[1,0,1] neg_lo:[0,0,1] neg_hi:[0,0,1]
	s_nop 0
	v_mov_b32_e32 v202, v213
	v_mov_b32_e32 v209, v203
	v_pk_mul_f32 v[202:203], v[214:215], v[202:203] op_sel:[1,0] op_sel_hi:[0,0]
	v_pk_fma_f32 v[204:205], v[214:215], v[212:213], v[202:203] op_sel_hi:[1,0,1] neg_hi:[0,0,1]
	s_nop 0
	v_add_u32_e32 v202, 0x818, v181
	ds_read2_b64 v[210:213], v202 offset1:1
	s_waitcnt lgkmcnt(0)
	v_pk_mul_f32 v[214:215], v[216:217], v[210:211] op_sel:[1,1] op_sel_hi:[0,1]
	v_pk_fma_f32 v[202:203], v[216:217], v[210:211], v[214:215]
	v_pk_fma_f32 v[210:211], v[216:217], v[210:211], v[214:215] op_sel_hi:[1,0,1] neg_lo:[0,0,1] neg_hi:[0,0,1]
	s_nop 0
	v_mov_b32_e32 v210, v213
	v_mov_b32_e32 v203, v211
	v_pk_mul_f32 v[210:211], v[218:219], v[210:211] op_sel:[1,0] op_sel_hi:[0,0]
	v_pk_fma_f32 v[216:217], v[218:219], v[212:213], v[210:211] op_sel_hi:[1,0,1] neg_hi:[0,0,1]
	s_nop 0
	v_add_u32_e32 v210, 0x828, v181
	ds_read2_b64 v[218:221], v210 offset1:1
	s_waitcnt lgkmcnt(0)
	v_pk_mul_f32 v[210:211], v[222:223], v[218:219] op_sel:[1,1] op_sel_hi:[0,1]
	v_pk_fma_f32 v[214:215], v[222:223], v[218:219], v[210:211]
	v_pk_fma_f32 v[210:211], v[222:223], v[218:219], v[210:211] op_sel_hi:[1,0,1] neg_lo:[0,0,1] neg_hi:[0,0,1]
	s_nop 0
	v_mov_b32_e32 v210, v221
	v_mov_b32_e32 v215, v211
	v_pk_mul_f32 v[210:211], v[224:225], v[210:211] op_sel:[1,0] op_sel_hi:[0,0]
	v_pk_fma_f32 v[212:213], v[224:225], v[220:221], v[210:211] op_sel_hi:[1,0,1] neg_hi:[0,0,1]
	s_nop 0
	v_add_u32_e32 v210, 0x838, v181
	ds_read2_b64 v[218:221], v210 offset1:1
	s_waitcnt lgkmcnt(0)
	v_pk_mul_f32 v[222:223], v[226:227], v[218:219] op_sel:[1,1] op_sel_hi:[0,1]
	v_pk_fma_f32 v[210:211], v[226:227], v[218:219], v[222:223]
	v_pk_fma_f32 v[218:219], v[226:227], v[218:219], v[222:223] op_sel_hi:[1,0,1] neg_lo:[0,0,1] neg_hi:[0,0,1]
	s_nop 0
	v_mov_b32_e32 v218, v221
	v_mov_b32_e32 v211, v219
	v_pk_mul_f32 v[218:219], v[228:229], v[218:219] op_sel:[1,0] op_sel_hi:[0,0]
	v_pk_fma_f32 v[224:225], v[228:229], v[220:221], v[218:219] op_sel_hi:[1,0,1] neg_hi:[0,0,1]
	s_nop 0
	v_add_u32_e32 v218, 0x848, v181
	ds_read2_b64 v[226:229], v218 offset1:1
	s_waitcnt lgkmcnt(0)
	v_pk_mul_f32 v[218:219], v[230:231], v[226:227] op_sel:[1,1] op_sel_hi:[0,1]
	v_pk_fma_f32 v[222:223], v[230:231], v[226:227], v[218:219]
	v_pk_fma_f32 v[218:219], v[230:231], v[226:227], v[218:219] op_sel_hi:[1,0,1] neg_lo:[0,0,1] neg_hi:[0,0,1]
	s_nop 0
	v_mov_b32_e32 v218, v229
	v_mov_b32_e32 v223, v219
	v_pk_mul_f32 v[218:219], v[236:237], v[218:219] op_sel:[1,0] op_sel_hi:[0,0]
	v_pk_fma_f32 v[220:221], v[236:237], v[228:229], v[218:219] op_sel_hi:[1,0,1] neg_hi:[0,0,1]
	s_nop 0
	v_add_u32_e32 v218, 0x858, v181
	ds_read2_b64 v[226:229], v218 offset1:1
	s_waitcnt lgkmcnt(0)
	v_pk_mul_f32 v[230:231], v[238:239], v[226:227] op_sel:[1,1] op_sel_hi:[0,1]
	v_pk_fma_f32 v[218:219], v[238:239], v[226:227], v[230:231]
	v_pk_fma_f32 v[226:227], v[238:239], v[226:227], v[230:231] op_sel_hi:[1,0,1] neg_lo:[0,0,1] neg_hi:[0,0,1]
	s_nop 0
	v_mov_b32_e32 v226, v229
	v_mov_b32_e32 v219, v227
	v_pk_mul_f32 v[226:227], v[242:243], v[226:227] op_sel:[1,0] op_sel_hi:[0,0]
	v_pk_fma_f32 v[230:231], v[242:243], v[228:229], v[226:227] op_sel_hi:[1,0,1] neg_hi:[0,0,1]
	s_nop 0
	v_add_u32_e32 v226, 0x868, v181
	ds_read2_b64 v[236:239], v226 offset1:1
	s_waitcnt lgkmcnt(0)
	v_pk_mul_f32 v[226:227], v[244:245], v[236:237] op_sel:[1,1] op_sel_hi:[0,1]
	v_pk_fma_f32 v[228:229], v[244:245], v[236:237], v[226:227]
	v_pk_fma_f32 v[226:227], v[244:245], v[236:237], v[226:227] op_sel_hi:[1,0,1] neg_lo:[0,0,1] neg_hi:[0,0,1]
	s_nop 0
	v_mov_b32_e32 v226, v239
	v_pk_mul_f32 v[236:237], v[246:247], v[226:227] op_sel:[1,0] op_sel_hi:[0,0]
	v_mov_b32_e32 v229, v227
	v_pk_fma_f32 v[226:227], v[246:247], v[238:239], v[236:237] op_sel_hi:[1,0,1] neg_hi:[0,0,1]
	s_nop 0
	ds_read_b64 v[236:237], v181 offset:2168
	v_bfe_i32 v181, v233, 0, 16
	v_lshl_add_u32 v181, v181, 8, v235
	s_waitcnt lgkmcnt(0)
	v_pk_mul_f32 v[238:239], v[206:207], v[236:237] op_sel:[1,1] op_sel_hi:[0,1]
	v_pk_fma_f32 v[242:243], v[206:207], v[236:237], v[238:239] op_sel_hi:[1,0,1] neg_hi:[0,0,1]
	s_nop 0
	v_pk_add_f32 v[206:207], v[200:201], v[224:225]
	v_pk_add_f32 v[200:201], v[200:201], v[224:225] neg_lo:[0,1] neg_hi:[0,1]
	v_pk_add_f32 v[224:225], v[216:217], v[230:231]
	v_pk_add_f32 v[216:217], v[216:217], v[230:231] neg_lo:[0,1] neg_hi:[0,1]
	s_nop 0
	v_xor_b32_e32 v230, 0x80000000, v217
	v_mov_b32_e32 v231, v216
	v_pk_add_f32 v[216:217], v[206:207], v[224:225]
	v_pk_add_f32 v[206:207], v[206:207], v[224:225] neg_lo:[0,1] neg_hi:[0,1]
	v_pk_add_f32 v[224:225], v[208:209], v[222:223]
	v_pk_add_f32 v[208:209], v[208:209], v[222:223] neg_lo:[0,1] neg_hi:[0,1]
	v_pk_add_f32 v[222:223], v[214:215], v[228:229]
	v_pk_add_f32 v[214:215], v[214:215], v[228:229] neg_lo:[0,1] neg_hi:[0,1]
	v_pk_add_f32 v[236:237], v[200:201], v[230:231]
	v_xor_b32_e32 v228, 0x80000000, v215
	v_mov_b32_e32 v229, v214
	v_pk_add_f32 v[214:215], v[224:225], v[222:223]
	v_pk_add_f32 v[222:223], v[224:225], v[222:223] neg_lo:[0,1] neg_hi:[0,1]
	v_pk_add_f32 v[224:225], v[204:205], v[220:221]
	v_pk_add_f32 v[204:205], v[204:205], v[220:221] neg_lo:[0,1] neg_hi:[0,1]
	v_pk_add_f32 v[220:221], v[212:213], v[226:227]
	v_pk_add_f32 v[212:213], v[212:213], v[226:227] neg_lo:[0,1] neg_hi:[0,1]
	v_pk_add_f32 v[200:201], v[200:201], v[230:231] neg_lo:[0,1] neg_hi:[0,1]
	v_pk_add_f32 v[230:231], v[208:209], v[228:229]
	v_xor_b32_e32 v226, 0x80000000, v213
	v_mov_b32_e32 v227, v212
	v_pk_add_f32 v[212:213], v[224:225], v[220:221]
	v_pk_add_f32 v[220:221], v[224:225], v[220:221] neg_lo:[0,1] neg_hi:[0,1]
	v_pk_add_f32 v[224:225], v[202:203], v[218:219]
	v_pk_add_f32 v[202:203], v[202:203], v[218:219] neg_lo:[0,1] neg_hi:[0,1]
	v_pk_add_f32 v[218:219], v[210:211], v[242:243]
	v_pk_add_f32 v[210:211], v[210:211], v[242:243] neg_lo:[0,1] neg_hi:[0,1]
	v_pk_add_f32 v[208:209], v[208:209], v[228:229] neg_lo:[0,1] neg_hi:[0,1]
	v_pk_add_f32 v[228:229], v[204:205], v[226:227]
	v_pk_add_f32 v[204:205], v[204:205], v[226:227] neg_lo:[0,1] neg_hi:[0,1]
	v_xor_b32_e32 v226, 0x80000000, v211
	v_mov_b32_e32 v227, v210
	v_pk_add_f32 v[210:211], v[224:225], v[218:219]
	v_pk_add_f32 v[218:219], v[224:225], v[218:219] neg_lo:[0,1] neg_hi:[0,1]
	v_pk_mul_f32 v[224:225], v[230:231], s[24:25] op_sel_hi:[1,0]
	v_pk_add_f32 v[238:239], v[202:203], v[226:227]
	v_pk_add_f32 v[202:203], v[202:203], v[226:227] neg_lo:[0,1] neg_hi:[0,1]
	v_pk_fma_f32 v[226:227], v[230:231], s[26:27], v[224:225] op_sel:[0,0,1] op_sel_hi:[1,0,0] neg_lo:[0,0,1]
	s_nop 0
	v_pk_mul_f32 v[224:225], v[222:223], s[28:29] op_sel_hi:[1,0]
	s_nop 0
	v_pk_fma_f32 v[230:231], v[222:223], s[28:29], v[224:225] op_sel:[0,0,1] op_sel_hi:[1,0,0] neg_lo:[0,0,1]
	v_pk_mul_f32 v[224:225], v[208:209], s[26:27] op_sel_hi:[1,0]
	v_pk_fma_f32 v[242:243], v[208:209], s[24:25], v[224:225] op_sel:[0,0,1] op_sel_hi:[1,0,0] neg_lo:[0,0,1]
	s_nop 0
	v_pk_mul_f32 v[208:209], v[228:229], s[28:29] op_sel_hi:[1,0]
	s_nop 0
	v_pk_fma_f32 v[224:225], v[228:229], s[28:29], v[208:209] op_sel:[0,0,1] op_sel_hi:[1,0,0] neg_lo:[0,0,1]
	s_nop 0
	v_pk_fma_f32 v[208:209], v[220:221], 0, v[220:221] op_sel:[0,0,1] op_sel_hi:[1,0,0] neg_lo:[0,0,1]
	s_nop 0
	v_pk_mul_f32 v[220:221], v[204:205], s[30:31] op_sel_hi:[1,0]
	s_nop 0
	v_pk_fma_f32 v[228:229], v[204:205], s[30:31], v[220:221] op_sel:[0,0,1] op_sel_hi:[1,0,0] neg_hi:[0,0,1]
	v_pk_mul_f32 v[220:221], v[238:239], s[26:27] op_sel_hi:[1,0]
	v_pk_fma_f32 v[244:245], v[238:239], s[24:25], v[220:221] op_sel:[0,0,1] op_sel_hi:[1,0,0] neg_lo:[0,0,1]
	s_mov_b32 s25, s34
	v_pk_mul_f32 v[220:221], v[218:219], s[30:31] op_sel_hi:[1,0]
	v_pk_add_f32 v[204:205], v[200:201], v[228:229]
	v_pk_fma_f32 v[238:239], v[218:219], s[30:31], v[220:221] op_sel:[0,0,1] op_sel_hi:[1,0,0] neg_hi:[0,0,1]
	v_pk_add_f32 v[200:201], v[200:201], v[228:229] neg_lo:[0,1] neg_hi:[0,1]
	v_pk_mul_f32 v[218:219], v[202:203], s[34:35] op_sel_hi:[0,1]
	v_pk_fma_f32 v[202:203], v[202:203], s[24:25], v[218:219] op_sel:[1,0,0]
	v_pk_add_f32 v[218:219], v[216:217], v[212:213]
	v_pk_add_f32 v[212:213], v[216:217], v[212:213] neg_lo:[0,1] neg_hi:[0,1]
	v_pk_add_f32 v[216:217], v[214:215], v[210:211]
	v_pk_add_f32 v[210:211], v[214:215], v[210:211] neg_lo:[0,1] neg_hi:[0,1]
	v_pk_add_f32 v[222:223], v[230:231], v[238:239] neg_lo:[0,1] neg_hi:[0,1]
	v_xor_b32_e32 v214, 0x80000000, v211
	v_mov_b32_e32 v215, v210
	v_pk_add_f32 v[210:211], v[218:219], v[216:217]
	v_pk_add_f32 v[220:221], v[212:213], v[214:215]
	v_pk_add_f32 v[216:217], v[218:219], v[216:217] neg_lo:[0,1] neg_hi:[0,1]
	v_pk_add_f32 v[212:213], v[212:213], v[214:215] neg_lo:[0,1] neg_hi:[0,1]
	v_pk_add_f32 v[214:215], v[236:237], v[224:225]
	v_pk_add_f32 v[218:219], v[236:237], v[224:225] neg_lo:[0,1] neg_hi:[0,1]
	v_pk_add_f32 v[224:225], v[226:227], v[244:245]
	v_pk_add_f32 v[226:227], v[226:227], v[244:245] neg_lo:[0,1] neg_hi:[0,1]
	s_nop 0
	v_xor_b32_e32 v236, 0x80000000, v227
	v_mov_b32_e32 v237, v226
	v_pk_add_f32 v[226:227], v[214:215], v[224:225]
	v_pk_add_f32 v[214:215], v[214:215], v[224:225] neg_lo:[0,1] neg_hi:[0,1]
	v_pk_add_f32 v[224:225], v[206:207], v[208:209]
	v_pk_add_f32 v[206:207], v[206:207], v[208:209] neg_lo:[0,1] neg_hi:[0,1]
	v_pk_add_f32 v[208:209], v[230:231], v[238:239]
	v_xor_b32_e32 v230, 0x80000000, v223
	v_mov_b32_e32 v231, v222
	v_pk_add_f32 v[222:223], v[224:225], v[208:209]
	v_pk_add_f32 v[208:209], v[224:225], v[208:209] neg_lo:[0,1] neg_hi:[0,1]
	v_pk_add_f32 v[224:225], v[242:243], v[202:203]
	v_pk_add_f32 v[202:203], v[242:243], v[202:203] neg_lo:[0,1] neg_hi:[0,1]
	v_pk_add_f32 v[244:245], v[218:219], v[236:237]
	v_xor_b32_e32 v228, 0x80000000, v203
	v_mov_b32_e32 v229, v202
	v_pk_add_f32 v[202:203], v[204:205], v[224:225]
	v_pk_add_f32 v[204:205], v[204:205], v[224:225] neg_lo:[0,1] neg_hi:[0,1]
	v_lshlrev_b32_e32 v225, 3, v181
	v_ashrrev_i32_e32 v181, 4, v181
	v_add_u32_e32 v224, s57, v234
	v_lshlrev_b32_e32 v181, 3, v181
	v_add3_u32 v181, v224, v225, v181
	v_pk_add_f32 v[218:219], v[218:219], v[236:237] neg_lo:[0,1] neg_hi:[0,1]
	v_pk_add_f32 v[236:237], v[206:207], v[230:231]
	v_pk_add_f32 v[206:207], v[206:207], v[230:231] neg_lo:[0,1] neg_hi:[0,1]
	v_pk_add_f32 v[230:231], v[200:201], v[228:229]
	v_pk_add_f32 v[200:201], v[200:201], v[228:229] neg_lo:[0,1] neg_hi:[0,1]
	ds_write2_b64 v181, v[210:211], v[226:227] offset1:17
	ds_write2_b64 v181, v[222:223], v[202:203] offset0:34 offset1:51
	ds_write2_b64 v181, v[220:221], v[244:245] offset0:68 offset1:85
	ds_write2_b64 v181, v[236:237], v[230:231] offset0:102 offset1:119
	ds_write2_b64 v181, v[216:217], v[214:215] offset0:136 offset1:153
	ds_write2_b64 v181, v[208:209], v[204:205] offset0:170 offset1:187
	ds_write2_b64 v181, v[212:213], v[218:219] offset0:204 offset1:221
	ds_write2_b64 v181, v[206:207], v[200:201] offset0:238 offset1:255

.LBB0_370:
	s_or_b64 exec, exec, s[2:3]
	v_mov_b32_e32 v200, v180
	s_waitcnt lgkmcnt(0)
	s_barrier
	s_nop 0
	v_cmp_gt_i32_e32 vcc, s56, v200
	s_and_saveexec_b64 s[2:3], vcc
	s_cbranch_execz .LBB0_372
	v_ashrrev_i32_e32 v181, 31, v200
	v_add_u32_sdwa v181, v200, v181 dst_sel:DWORD dst_unused:UNUSED_PAD src0_sel:DWORD src1_sel:BYTE_3
	v_ashrrev_i32_e32 v181, 8, v181
	v_mul_i32_i24_e32 v201, 0x100, v181
	v_sub_u32_e32 v200, v200, v201
	v_ashrrev_i16_e32 v201, 15, v200
	v_lshrrev_b16_e32 v201, 12, v201
	v_add_u16_e32 v201, v200, v201
	v_ashrrev_i16_e32 v237, 4, v201
	v_and_b32_e32 v201, -16, v201
	v_mul_i32_i24_e32 v181, 0x1100, v181
	v_sub_u16_e32 v204, v200, v201
	v_lshlrev_b32_e32 v238, 3, v181
	v_lshlrev_b32_e32 v201, 3, v200
	v_ashrrev_i32_e32 v200, 4, v200
	v_add_u32_e32 v181, s57, v238
	v_lshlrev_b32_e32 v200, 3, v200
	v_add3_u32 v181, v181, v201, v200
	v_bfe_i32 v239, v204, 0, 16
	ds_read_b64 v[200:201], v181
	ds_read_b64 v[202:203], v181 offset:2176
	ds_read_b64 v[214:215], v181 offset:4352
	ds_read_b64 v[216:217], v181 offset:6528
	ds_read_b64 v[218:219], v181 offset:8704
	ds_read_b64 v[222:223], v181 offset:10880
	ds_read_b64 v[224:225], v181 offset:13056
	ds_read_b64 v[226:227], v181 offset:15232
	ds_read_b64 v[228:229], v181 offset:17408
	ds_read_b64 v[230:231], v181 offset:19584
	ds_read_b64 v[242:243], v181 offset:21760
	ds_read_b64 v[244:245], v181 offset:23936
	ds_read_b64 v[246:247], v181 offset:26112
	ds_read_b64 v[248:249], v181 offset:28288
	ds_read_b64 v[250:251], v181 offset:30464
	ds_read_b64 v[206:207], v181 offset:32640
	v_mad_i32_i24 v181, v239, s27, 0
	v_add_u32_e32 v204, 0x808, v181
	ds_read2_b64 v[210:213], v204 offset1:1
	s_mov_b32 s61, s34
	s_mov_b32 s35, s24
	s_waitcnt lgkmcnt(0)
	v_pk_mul_f32 v[204:205], v[202:203], v[210:211] op_sel:[1,1] op_sel_hi:[1,0]
	s_nop 0
	v_pk_fma_f32 v[208:209], v[202:203], v[210:211], v[204:205] op_sel_hi:[0,1,1] neg_lo:[0,0,1]
	v_pk_mul_f32 v[202:203], v[214:215], v[212:213] op_sel:[1,1] op_sel_hi:[1,0]
	s_nop 0
	v_pk_fma_f32 v[204:205], v[214:215], v[212:213], v[202:203] op_sel_hi:[0,1,1] neg_lo:[0,0,1]
	v_add_u32_e32 v202, 0x818, v181
	ds_read2_b64 v[210:213], v202 offset1:1
	s_waitcnt lgkmcnt(0)
	v_pk_mul_f32 v[214:215], v[216:217], v[210:211] op_sel:[1,1] op_sel_hi:[1,0]
	s_nop 0
	v_pk_fma_f32 v[202:203], v[216:217], v[210:211], v[214:215] op_sel_hi:[0,1,1] neg_lo:[0,0,1]
	v_pk_mul_f32 v[210:211], v[218:219], v[212:213] op_sel:[1,1] op_sel_hi:[1,0]
	s_nop 0
	v_pk_fma_f32 v[216:217], v[218:219], v[212:213], v[210:211] op_sel_hi:[0,1,1] neg_lo:[0,0,1]
	v_add_u32_e32 v210, 0x828, v181
	ds_read2_b64 v[218:221], v210 offset1:1
	s_waitcnt lgkmcnt(0)
	v_pk_mul_f32 v[210:211], v[222:223], v[218:219] op_sel:[1,1] op_sel_hi:[1,0]
	s_nop 0
	v_pk_fma_f32 v[214:215], v[222:223], v[218:219], v[210:211] op_sel_hi:[0,1,1] neg_lo:[0,0,1]
	v_pk_mul_f32 v[210:211], v[224:225], v[220:221] op_sel:[1,1] op_sel_hi:[1,0]
	s_nop 0
	v_pk_fma_f32 v[212:213], v[224:225], v[220:221], v[210:211] op_sel_hi:[0,1,1] neg_lo:[0,0,1]
	v_add_u32_e32 v210, 0x838, v181
	ds_read2_b64 v[218:221], v210 offset1:1
	s_waitcnt lgkmcnt(0)
	v_pk_mul_f32 v[222:223], v[226:227], v[218:219] op_sel:[1,1] op_sel_hi:[1,0]
	s_nop 0
	v_pk_fma_f32 v[210:211], v[226:227], v[218:219], v[222:223] op_sel_hi:[0,1,1] neg_lo:[0,0,1]
	v_pk_mul_f32 v[218:219], v[228:229], v[220:221] op_sel:[1,1] op_sel_hi:[1,0]
	s_nop 0
	v_pk_fma_f32 v[224:225], v[228:229], v[220:221], v[218:219] op_sel_hi:[0,1,1] neg_lo:[0,0,1]
	v_add_u32_e32 v218, 0x848, v181
	ds_read2_b64 v[226:229], v218 offset1:1
	s_waitcnt lgkmcnt(0)
	v_pk_mul_f32 v[218:219], v[230:231], v[226:227] op_sel:[1,1] op_sel_hi:[1,0]
	s_nop 0
	v_pk_fma_f32 v[222:223], v[230:231], v[226:227], v[218:219] op_sel_hi:[0,1,1] neg_lo:[0,0,1]
	v_pk_mul_f32 v[218:219], v[242:243], v[228:229] op_sel:[1,1] op_sel_hi:[1,0]
	s_nop 0
	v_pk_fma_f32 v[220:221], v[242:243], v[228:229], v[218:219] op_sel_hi:[0,1,1] neg_lo:[0,0,1]
	v_add_u32_e32 v218, 0x858, v181
	ds_read2_b64 v[226:229], v218 offset1:1
	s_waitcnt lgkmcnt(0)
	v_pk_mul_f32 v[230:231], v[244:245], v[226:227] op_sel:[1,1] op_sel_hi:[1,0]
	s_nop 0
	v_pk_fma_f32 v[218:219], v[244:245], v[226:227], v[230:231] op_sel_hi:[0,1,1] neg_lo:[0,0,1]
	v_pk_mul_f32 v[226:227], v[246:247], v[228:229] op_sel:[1,1] op_sel_hi:[1,0]
	s_nop 0
	v_pk_fma_f32 v[230:231], v[246:247], v[228:229], v[226:227] op_sel_hi:[0,1,1] neg_lo:[0,0,1]
	v_add_u32_e32 v226, 0x868, v181
	ds_read2_b64 v[242:245], v226 offset1:1
	s_waitcnt lgkmcnt(0)
	v_pk_mul_f32 v[226:227], v[248:249], v[242:243] op_sel:[1,1] op_sel_hi:[1,0]
	s_nop 0
	v_pk_fma_f32 v[228:229], v[248:249], v[242:243], v[226:227] op_sel_hi:[0,1,1] neg_lo:[0,0,1]
	v_pk_mul_f32 v[242:243], v[250:251], v[244:245] op_sel:[1,1] op_sel_hi:[1,0]
	v_pk_fma_f32 v[226:227], v[250:251], v[244:245], v[242:243] op_sel_hi:[0,1,1] neg_lo:[0,0,1]
	ds_read_b64 v[242:243], v181 offset:2168
	v_bfe_i32 v181, v237, 0, 16
	v_lshl_add_u32 v181, v181, 8, v239
	s_waitcnt lgkmcnt(0)
	v_pk_mul_f32 v[244:245], v[206:207], v[242:243] op_sel:[1,1] op_sel_hi:[1,0]
	s_nop 0
	v_pk_fma_f32 v[246:247], v[206:207], v[242:243], v[244:245] op_sel_hi:[0,1,1] neg_lo:[0,0,1]
	v_pk_add_f32 v[206:207], v[200:201], v[224:225]
	v_pk_add_f32 v[200:201], v[200:201], v[224:225] neg_lo:[0,1] neg_hi:[0,1]
	v_pk_add_f32 v[224:225], v[216:217], v[230:231]
	v_pk_add_f32 v[216:217], v[216:217], v[230:231] neg_lo:[0,1] neg_hi:[0,1]
	s_nop 0
	v_xor_b32_e32 v231, 0x80000000, v216
	v_mov_b32_e32 v230, v217
	v_pk_add_f32 v[216:217], v[206:207], v[224:225]
	v_pk_add_f32 v[206:207], v[206:207], v[224:225] neg_lo:[0,1] neg_hi:[0,1]
	v_pk_add_f32 v[224:225], v[208:209], v[222:223]
	v_pk_add_f32 v[208:209], v[208:209], v[222:223] neg_lo:[0,1] neg_hi:[0,1]
	v_pk_add_f32 v[222:223], v[214:215], v[228:229]
	v_pk_add_f32 v[214:215], v[214:215], v[228:229] neg_lo:[0,1] neg_hi:[0,1]
	v_pk_add_f32 v[242:243], v[200:201], v[230:231]
	v_xor_b32_e32 v229, 0x80000000, v214
	v_mov_b32_e32 v228, v215
	v_pk_add_f32 v[214:215], v[224:225], v[222:223]
	v_pk_add_f32 v[222:223], v[224:225], v[222:223] neg_lo:[0,1] neg_hi:[0,1]
	v_pk_add_f32 v[224:225], v[204:205], v[220:221]
	v_pk_add_f32 v[204:205], v[204:205], v[220:221] neg_lo:[0,1] neg_hi:[0,1]
	v_pk_add_f32 v[220:221], v[212:213], v[226:227]
	v_pk_add_f32 v[212:213], v[212:213], v[226:227] neg_lo:[0,1] neg_hi:[0,1]
	v_pk_add_f32 v[200:201], v[200:201], v[230:231] neg_lo:[0,1] neg_hi:[0,1]
	v_pk_add_f32 v[230:231], v[208:209], v[228:229]
	v_xor_b32_e32 v227, 0x80000000, v212
	v_mov_b32_e32 v226, v213
	v_pk_add_f32 v[212:213], v[224:225], v[220:221]
	v_pk_add_f32 v[220:221], v[224:225], v[220:221] neg_lo:[0,1] neg_hi:[0,1]
	v_pk_add_f32 v[224:225], v[202:203], v[218:219]
	v_pk_add_f32 v[202:203], v[202:203], v[218:219] neg_lo:[0,1] neg_hi:[0,1]
	v_pk_add_f32 v[218:219], v[210:211], v[246:247]
	v_pk_add_f32 v[210:211], v[210:211], v[246:247] neg_lo:[0,1] neg_hi:[0,1]
	v_pk_add_f32 v[208:209], v[208:209], v[228:229] neg_lo:[0,1] neg_hi:[0,1]
	v_pk_add_f32 v[228:229], v[204:205], v[226:227]
	v_pk_add_f32 v[204:205], v[204:205], v[226:227] neg_lo:[0,1] neg_hi:[0,1]
	v_xor_b32_e32 v227, 0x80000000, v210
	v_mov_b32_e32 v226, v211
	v_pk_add_f32 v[210:211], v[224:225], v[218:219]
	v_pk_add_f32 v[218:219], v[224:225], v[218:219] neg_lo:[0,1] neg_hi:[0,1]
	v_pk_mul_f32 v[224:225], v[230:231], s[24:25] op_sel_hi:[1,0]
	v_pk_add_f32 v[244:245], v[202:203], v[226:227]
	v_pk_add_f32 v[202:203], v[202:203], v[226:227] neg_lo:[0,1] neg_hi:[0,1]
	v_pk_fma_f32 v[226:227], v[230:231], s[26:27], v[224:225] op_sel:[0,0,1] op_sel_hi:[1,0,0] neg_hi:[0,0,1]
	s_nop 0
	v_pk_mul_f32 v[224:225], v[222:223], s[28:29] op_sel_hi:[1,0]
	s_nop 0
	v_pk_fma_f32 v[230:231], v[222:223], s[28:29], v[224:225] op_sel:[0,0,1] op_sel_hi:[1,0,0] neg_hi:[0,0,1]
	v_pk_mul_f32 v[224:225], v[208:209], s[26:27] op_sel_hi:[1,0]
	v_pk_fma_f32 v[246:247], v[208:209], s[24:25], v[224:225] op_sel:[0,0,1] op_sel_hi:[1,0,0] neg_hi:[0,0,1]
	s_nop 0
	v_pk_mul_f32 v[208:209], v[228:229], s[28:29] op_sel_hi:[1,0]
	s_nop 0
	v_pk_fma_f32 v[224:225], v[228:229], s[28:29], v[208:209] op_sel:[0,0,1] op_sel_hi:[1,0,0] neg_hi:[0,0,1]
	s_nop 0
	v_pk_fma_f32 v[208:209], v[220:221], 0, v[220:221] op_sel:[0,0,1] op_sel_hi:[1,0,0] neg_hi:[0,0,1]
	s_nop 0
	v_pk_mul_f32 v[220:221], v[204:205], s[30:31] op_sel_hi:[1,0]
	s_nop 0
	v_pk_fma_f32 v[228:229], v[204:205], s[30:31], v[220:221] op_sel:[0,0,1] op_sel_hi:[1,0,0] neg_lo:[0,0,1]
	v_pk_mul_f32 v[220:221], v[244:245], s[26:27] op_sel_hi:[1,0]
	v_pk_fma_f32 v[248:249], v[244:245], s[24:25], v[220:221] op_sel:[0,0,1] op_sel_hi:[1,0,0] neg_hi:[0,0,1]
	v_pk_add_f32 v[204:205], v[200:201], v[228:229]
	v_pk_mul_f32 v[220:221], v[218:219], s[30:31] op_sel_hi:[1,0]
	v_pk_add_f32 v[200:201], v[200:201], v[228:229] neg_lo:[0,1] neg_hi:[0,1]
	v_pk_fma_f32 v[244:245], v[218:219], s[30:31], v[220:221] op_sel:[0,0,1] op_sel_hi:[1,0,0] neg_lo:[0,0,1]
	s_nop 0
	v_pk_mul_f32 v[218:219], v[202:203], s[60:61] op_sel:[1,0]
	v_pk_add_f32 v[222:223], v[230:231], v[244:245] neg_lo:[0,1] neg_hi:[0,1]
	v_pk_fma_f32 v[202:203], v[202:203], s[34:35], v[218:219] op_sel_hi:[0,1,1]
	v_pk_add_f32 v[218:219], v[216:217], v[212:213]
	v_pk_add_f32 v[212:213], v[216:217], v[212:213] neg_lo:[0,1] neg_hi:[0,1]
	v_pk_add_f32 v[216:217], v[214:215], v[210:211]
	v_pk_add_f32 v[210:211], v[214:215], v[210:211] neg_lo:[0,1] neg_hi:[0,1]
	s_nop 0
	v_xor_b32_e32 v215, 0x80000000, v210
	v_mov_b32_e32 v214, v211
	v_pk_add_f32 v[210:211], v[218:219], v[216:217]
	v_pk_add_f32 v[220:221], v[212:213], v[214:215]
	v_pk_add_f32 v[216:217], v[218:219], v[216:217] neg_lo:[0,1] neg_hi:[0,1]
	v_pk_add_f32 v[212:213], v[212:213], v[214:215] neg_lo:[0,1] neg_hi:[0,1]
	v_pk_add_f32 v[214:215], v[242:243], v[224:225]
	v_pk_add_f32 v[218:219], v[242:243], v[224:225] neg_lo:[0,1] neg_hi:[0,1]
	v_pk_add_f32 v[224:225], v[226:227], v[248:249]
	v_pk_add_f32 v[226:227], v[226:227], v[248:249] neg_lo:[0,1] neg_hi:[0,1]
	s_nop 0
	v_xor_b32_e32 v243, 0x80000000, v226
	v_mov_b32_e32 v242, v227
	v_pk_add_f32 v[226:227], v[214:215], v[224:225]
	v_pk_add_f32 v[214:215], v[214:215], v[224:225] neg_lo:[0,1] neg_hi:[0,1]
	v_pk_add_f32 v[224:225], v[206:207], v[208:209]
	v_pk_add_f32 v[206:207], v[206:207], v[208:209] neg_lo:[0,1] neg_hi:[0,1]
	v_pk_add_f32 v[208:209], v[230:231], v[244:245]
	v_xor_b32_e32 v231, 0x80000000, v222
	v_mov_b32_e32 v230, v223
	v_pk_add_f32 v[222:223], v[224:225], v[208:209]
	v_pk_add_f32 v[208:209], v[224:225], v[208:209] neg_lo:[0,1] neg_hi:[0,1]
	v_pk_add_f32 v[224:225], v[246:247], v[202:203]
	v_pk_add_f32 v[202:203], v[246:247], v[202:203] neg_lo:[0,1] neg_hi:[0,1]
	v_pk_add_f32 v[248:249], v[218:219], v[242:243]
	v_xor_b32_e32 v229, 0x80000000, v202
	v_mov_b32_e32 v228, v203
	v_pk_add_f32 v[202:203], v[204:205], v[224:225]
	v_pk_add_f32 v[204:205], v[204:205], v[224:225] neg_lo:[0,1] neg_hi:[0,1]
	v_lshlrev_b32_e32 v225, 3, v181
	v_ashrrev_i32_e32 v181, 4, v181
	v_add_u32_e32 v224, 0, v238
	v_lshlrev_b32_e32 v181, 3, v181
	v_add3_u32 v181, v224, v225, v181
	v_pk_add_f32 v[218:219], v[218:219], v[242:243] neg_lo:[0,1] neg_hi:[0,1]
	v_pk_add_f32 v[242:243], v[206:207], v[230:231]
	v_pk_add_f32 v[206:207], v[206:207], v[230:231] neg_lo:[0,1] neg_hi:[0,1]
	v_pk_add_f32 v[230:231], v[200:201], v[228:229]
	v_pk_add_f32 v[200:201], v[200:201], v[228:229] neg_lo:[0,1] neg_hi:[0,1]
	v_add_u32_e32 v224, 0x1800, v181
	v_add_u32_e32 v181, 0x1c00, v181
	ds_write2_b64 v224, v[210:211], v[226:227] offset0:16 offset1:33
	ds_write2_b64 v224, v[222:223], v[202:203] offset0:50 offset1:67
	ds_write2_b64 v224, v[220:221], v[248:249] offset0:84 offset1:101
	ds_write2_b64 v224, v[242:243], v[230:231] offset0:118 offset1:135
	ds_write2_b64 v224, v[216:217], v[214:215] offset0:152 offset1:169
	ds_write2_b64 v224, v[208:209], v[204:205] offset0:186 offset1:203
	ds_write2_b64 v224, v[212:213], v[218:219] offset0:220 offset1:237
	ds_write2_b64 v181, v[206:207], v[200:201] offset0:126 offset1:143

.LBB0_376:
	s_or_b64 exec, exec, s[2:3]
	v_mov_b32_e32 v200, v180
	s_waitcnt lgkmcnt(0)
	s_barrier
	s_nop 0
	v_cmp_gt_i32_e32 vcc, s56, v200
	s_and_saveexec_b64 s[2:3], vcc
	s_cbranch_execz .LBB0_378
	v_ashrrev_i32_e32 v181, 31, v200
	v_add_u32_sdwa v181, v200, v181 dst_sel:DWORD dst_unused:UNUSED_PAD src0_sel:DWORD src1_sel:BYTE_3
	v_ashrrev_i32_e32 v181, 8, v181
	v_mul_i32_i24_e32 v201, 0x100, v181
	v_sub_u32_e32 v200, v200, v201
	v_ashrrev_i16_e32 v201, 15, v200
	v_lshrrev_b16_e32 v201, 12, v201
	v_add_u16_e32 v201, v200, v201
	v_ashrrev_i16_e32 v237, 4, v201
	v_and_b32_e32 v201, -16, v201
	v_mul_i32_i24_e32 v181, 0x1100, v181
	v_sub_u16_e32 v204, v200, v201
	v_lshlrev_b32_e32 v238, 3, v181
	v_lshlrev_b32_e32 v201, 3, v200
	v_ashrrev_i32_e32 v200, 4, v200
	v_add_u32_e32 v181, 0, v238
	v_lshlrev_b32_e32 v200, 3, v200
	v_add3_u32 v181, v181, v201, v200
	v_bfe_i32 v239, v204, 0, 16
	ds_read_b64 v[200:201], v181 offset:6272
	ds_read_b64 v[202:203], v181 offset:8448
	ds_read_b64 v[214:215], v181 offset:10624
	ds_read_b64 v[216:217], v181 offset:12800
	ds_read_b64 v[218:219], v181 offset:14976
	ds_read_b64 v[222:223], v181 offset:17152
	ds_read_b64 v[224:225], v181 offset:19328
	ds_read_b64 v[226:227], v181 offset:21504
	ds_read_b64 v[228:229], v181 offset:23680
	ds_read_b64 v[230:231], v181 offset:25856
	ds_read_b64 v[242:243], v181 offset:28032
	ds_read_b64 v[244:245], v181 offset:30208
	ds_read_b64 v[246:247], v181 offset:32384
	ds_read_b64 v[248:249], v181 offset:34560
	ds_read_b64 v[250:251], v181 offset:36736
	ds_read_b64 v[206:207], v181 offset:38912
	v_mad_i32_i24 v181, v239, s27, 0
	v_add_u32_e32 v204, 0x808, v181
	ds_read2_b64 v[210:213], v204 offset1:1
	s_mov_b32 s35, s60
	s_waitcnt lgkmcnt(0)
	v_pk_mul_f32 v[204:205], v[202:203], v[210:211] op_sel:[1,1] op_sel_hi:[0,1]
	v_pk_fma_f32 v[208:209], v[202:203], v[210:211], v[204:205]
	v_pk_fma_f32 v[202:203], v[202:203], v[210:211], v[204:205] op_sel_hi:[1,0,1] neg_lo:[0,0,1] neg_hi:[0,0,1]
	s_nop 0
	v_mov_b32_e32 v202, v213
	v_mov_b32_e32 v209, v203
	v_pk_mul_f32 v[202:203], v[214:215], v[202:203] op_sel:[1,0] op_sel_hi:[0,0]
	v_pk_fma_f32 v[204:205], v[214:215], v[212:213], v[202:203] op_sel_hi:[1,0,1] neg_hi:[0,0,1]
	s_nop 0
	v_add_u32_e32 v202, 0x818, v181
	ds_read2_b64 v[210:213], v202 offset1:1
	s_waitcnt lgkmcnt(0)
	v_pk_mul_f32 v[214:215], v[216:217], v[210:211] op_sel:[1,1] op_sel_hi:[0,1]
	v_pk_fma_f32 v[202:203], v[216:217], v[210:211], v[214:215]
	v_pk_fma_f32 v[210:211], v[216:217], v[210:211], v[214:215] op_sel_hi:[1,0,1] neg_lo:[0,0,1] neg_hi:[0,0,1]
	s_nop 0
	v_mov_b32_e32 v210, v213
	v_mov_b32_e32 v203, v211
	v_pk_mul_f32 v[210:211], v[218:219], v[210:211] op_sel:[1,0] op_sel_hi:[0,0]
	v_pk_fma_f32 v[216:217], v[218:219], v[212:213], v[210:211] op_sel_hi:[1,0,1] neg_hi:[0,0,1]
	s_nop 0
	v_add_u32_e32 v210, 0x828, v181
	ds_read2_b64 v[218:221], v210 offset1:1
	s_waitcnt lgkmcnt(0)
	v_pk_mul_f32 v[210:211], v[222:223], v[218:219] op_sel:[1,1] op_sel_hi:[0,1]
	v_pk_fma_f32 v[214:215], v[222:223], v[218:219], v[210:211]
	v_pk_fma_f32 v[210:211], v[222:223], v[218:219], v[210:211] op_sel_hi:[1,0,1] neg_lo:[0,0,1] neg_hi:[0,0,1]
	s_nop 0
	v_mov_b32_e32 v210, v221
	v_mov_b32_e32 v215, v211
	v_pk_mul_f32 v[210:211], v[224:225], v[210:211] op_sel:[1,0] op_sel_hi:[0,0]
	v_pk_fma_f32 v[212:213], v[224:225], v[220:221], v[210:211] op_sel_hi:[1,0,1] neg_hi:[0,0,1]
	s_nop 0
	v_add_u32_e32 v210, 0x838, v181
	ds_read2_b64 v[218:221], v210 offset1:1
	s_waitcnt lgkmcnt(0)
	v_pk_mul_f32 v[222:223], v[226:227], v[218:219] op_sel:[1,1] op_sel_hi:[0,1]
	v_pk_fma_f32 v[210:211], v[226:227], v[218:219], v[222:223]
	v_pk_fma_f32 v[218:219], v[226:227], v[218:219], v[222:223] op_sel_hi:[1,0,1] neg_lo:[0,0,1] neg_hi:[0,0,1]
	s_nop 0
	v_mov_b32_e32 v218, v221
	v_mov_b32_e32 v211, v219
	v_pk_mul_f32 v[218:219], v[228:229], v[218:219] op_sel:[1,0] op_sel_hi:[0,0]
	v_pk_fma_f32 v[224:225], v[228:229], v[220:221], v[218:219] op_sel_hi:[1,0,1] neg_hi:[0,0,1]
	s_nop 0
	v_add_u32_e32 v218, 0x848, v181
	ds_read2_b64 v[226:229], v218 offset1:1
	s_waitcnt lgkmcnt(0)
	v_pk_mul_f32 v[218:219], v[230:231], v[226:227] op_sel:[1,1] op_sel_hi:[0,1]
	v_pk_fma_f32 v[222:223], v[230:231], v[226:227], v[218:219]
	v_pk_fma_f32 v[218:219], v[230:231], v[226:227], v[218:219] op_sel_hi:[1,0,1] neg_lo:[0,0,1] neg_hi:[0,0,1]
	s_nop 0
	v_mov_b32_e32 v218, v229
	v_mov_b32_e32 v223, v219
	v_pk_mul_f32 v[218:219], v[242:243], v[218:219] op_sel:[1,0] op_sel_hi:[0,0]
	v_pk_fma_f32 v[220:221], v[242:243], v[228:229], v[218:219] op_sel_hi:[1,0,1] neg_hi:[0,0,1]
	s_nop 0
	v_add_u32_e32 v218, 0x858, v181
	ds_read2_b64 v[226:229], v218 offset1:1
	s_waitcnt lgkmcnt(0)
	v_pk_mul_f32 v[230:231], v[244:245], v[226:227] op_sel:[1,1] op_sel_hi:[0,1]
	v_pk_fma_f32 v[218:219], v[244:245], v[226:227], v[230:231]
	v_pk_fma_f32 v[226:227], v[244:245], v[226:227], v[230:231] op_sel_hi:[1,0,1] neg_lo:[0,0,1] neg_hi:[0,0,1]
	s_nop 0
	v_mov_b32_e32 v226, v229
	v_mov_b32_e32 v219, v227
	v_pk_mul_f32 v[226:227], v[246:247], v[226:227] op_sel:[1,0] op_sel_hi:[0,0]
	v_pk_fma_f32 v[230:231], v[246:247], v[228:229], v[226:227] op_sel_hi:[1,0,1] neg_hi:[0,0,1]
	s_nop 0
	v_add_u32_e32 v226, 0x868, v181
	ds_read2_b64 v[242:245], v226 offset1:1
	s_waitcnt lgkmcnt(0)
	v_pk_mul_f32 v[226:227], v[248:249], v[242:243] op_sel:[1,1] op_sel_hi:[0,1]
	v_pk_fma_f32 v[228:229], v[248:249], v[242:243], v[226:227]
	v_pk_fma_f32 v[226:227], v[248:249], v[242:243], v[226:227] op_sel_hi:[1,0,1] neg_lo:[0,0,1] neg_hi:[0,0,1]
	s_nop 0
	v_mov_b32_e32 v226, v245
	v_pk_mul_f32 v[242:243], v[250:251], v[226:227] op_sel:[1,0] op_sel_hi:[0,0]
	v_mov_b32_e32 v229, v227
	v_pk_fma_f32 v[226:227], v[250:251], v[244:245], v[242:243] op_sel_hi:[1,0,1] neg_hi:[0,0,1]
	s_nop 0
	ds_read_b64 v[242:243], v181 offset:2168
	v_bfe_i32 v181, v237, 0, 16
	v_lshl_add_u32 v181, v181, 8, v239
	s_waitcnt lgkmcnt(0)
	v_pk_mul_f32 v[244:245], v[206:207], v[242:243] op_sel:[1,1] op_sel_hi:[0,1]
	v_pk_fma_f32 v[246:247], v[206:207], v[242:243], v[244:245] op_sel_hi:[1,0,1] neg_hi:[0,0,1]
	s_nop 0
	v_pk_add_f32 v[206:207], v[200:201], v[224:225]
	v_pk_add_f32 v[200:201], v[200:201], v[224:225] neg_lo:[0,1] neg_hi:[0,1]
	v_pk_add_f32 v[224:225], v[216:217], v[230:231]
	v_pk_add_f32 v[216:217], v[216:217], v[230:231] neg_lo:[0,1] neg_hi:[0,1]
	s_nop 0
	v_xor_b32_e32 v230, 0x80000000, v217
	v_mov_b32_e32 v231, v216
	v_pk_add_f32 v[216:217], v[206:207], v[224:225]
	v_pk_add_f32 v[206:207], v[206:207], v[224:225] neg_lo:[0,1] neg_hi:[0,1]
	v_pk_add_f32 v[224:225], v[208:209], v[222:223]
	v_pk_add_f32 v[208:209], v[208:209], v[222:223] neg_lo:[0,1] neg_hi:[0,1]
	v_pk_add_f32 v[222:223], v[214:215], v[228:229]
	v_pk_add_f32 v[214:215], v[214:215], v[228:229] neg_lo:[0,1] neg_hi:[0,1]
	v_pk_add_f32 v[242:243], v[200:201], v[230:231]
	v_xor_b32_e32 v228, 0x80000000, v215
	v_mov_b32_e32 v229, v214
	v_pk_add_f32 v[214:215], v[224:225], v[222:223]
	v_pk_add_f32 v[222:223], v[224:225], v[222:223] neg_lo:[0,1] neg_hi:[0,1]
	v_pk_add_f32 v[224:225], v[204:205], v[220:221]
	v_pk_add_f32 v[204:205], v[204:205], v[220:221] neg_lo:[0,1] neg_hi:[0,1]
	v_pk_add_f32 v[220:221], v[212:213], v[226:227]
	v_pk_add_f32 v[212:213], v[212:213], v[226:227] neg_lo:[0,1] neg_hi:[0,1]
	v_pk_add_f32 v[200:201], v[200:201], v[230:231] neg_lo:[0,1] neg_hi:[0,1]
	v_pk_add_f32 v[230:231], v[208:209], v[228:229]
	v_xor_b32_e32 v226, 0x80000000, v213
	v_mov_b32_e32 v227, v212
	v_pk_add_f32 v[212:213], v[224:225], v[220:221]
	v_pk_add_f32 v[220:221], v[224:225], v[220:221] neg_lo:[0,1] neg_hi:[0,1]
	v_pk_add_f32 v[224:225], v[202:203], v[218:219]
	v_pk_add_f32 v[202:203], v[202:203], v[218:219] neg_lo:[0,1] neg_hi:[0,1]
	v_pk_add_f32 v[218:219], v[210:211], v[246:247]
	v_pk_add_f32 v[210:211], v[210:211], v[246:247] neg_lo:[0,1] neg_hi:[0,1]
	v_pk_add_f32 v[208:209], v[208:209], v[228:229] neg_lo:[0,1] neg_hi:[0,1]
	v_pk_add_f32 v[228:229], v[204:205], v[226:227]
	v_pk_add_f32 v[204:205], v[204:205], v[226:227] neg_lo:[0,1] neg_hi:[0,1]
	v_xor_b32_e32 v226, 0x80000000, v211
	v_mov_b32_e32 v227, v210
	v_pk_add_f32 v[210:211], v[224:225], v[218:219]
	v_pk_add_f32 v[218:219], v[224:225], v[218:219] neg_lo:[0,1] neg_hi:[0,1]
	v_pk_mul_f32 v[224:225], v[230:231], s[24:25] op_sel_hi:[1,0]
	v_pk_add_f32 v[244:245], v[202:203], v[226:227]
	v_pk_add_f32 v[202:203], v[202:203], v[226:227] neg_lo:[0,1] neg_hi:[0,1]
	v_pk_fma_f32 v[226:227], v[230:231], s[26:27], v[224:225] op_sel:[0,0,1] op_sel_hi:[1,0,0] neg_lo:[0,0,1]
	s_nop 0
	v_pk_mul_f32 v[224:225], v[222:223], s[28:29] op_sel_hi:[1,0]
	s_nop 0
	v_pk_fma_f32 v[230:231], v[222:223], s[28:29], v[224:225] op_sel:[0,0,1] op_sel_hi:[1,0,0] neg_lo:[0,0,1]
	v_pk_mul_f32 v[224:225], v[208:209], s[26:27] op_sel_hi:[1,0]
	v_pk_fma_f32 v[246:247], v[208:209], s[24:25], v[224:225] op_sel:[0,0,1] op_sel_hi:[1,0,0] neg_lo:[0,0,1]
	s_nop 0
	v_pk_mul_f32 v[208:209], v[228:229], s[28:29] op_sel_hi:[1,0]
	s_nop 0
	v_pk_fma_f32 v[224:225], v[228:229], s[28:29], v[208:209] op_sel:[0,0,1] op_sel_hi:[1,0,0] neg_lo:[0,0,1]
	s_nop 0
	v_pk_fma_f32 v[208:209], v[220:221], 0, v[220:221] op_sel:[0,0,1] op_sel_hi:[1,0,0] neg_lo:[0,0,1]
	s_nop 0
	v_pk_mul_f32 v[220:221], v[204:205], s[30:31] op_sel_hi:[1,0]
	s_nop 0
	v_pk_fma_f32 v[228:229], v[204:205], s[30:31], v[220:221] op_sel:[0,0,1] op_sel_hi:[1,0,0] neg_hi:[0,0,1]
	v_pk_mul_f32 v[220:221], v[244:245], s[26:27] op_sel_hi:[1,0]
	v_pk_fma_f32 v[248:249], v[244:245], s[24:25], v[220:221] op_sel:[0,0,1] op_sel_hi:[1,0,0] neg_lo:[0,0,1]
	s_mov_b32 s25, s34
	v_pk_mul_f32 v[220:221], v[218:219], s[30:31] op_sel_hi:[1,0]
	v_pk_add_f32 v[204:205], v[200:201], v[228:229]
	v_pk_fma_f32 v[244:245], v[218:219], s[30:31], v[220:221] op_sel:[0,0,1] op_sel_hi:[1,0,0] neg_hi:[0,0,1]
	v_pk_add_f32 v[200:201], v[200:201], v[228:229] neg_lo:[0,1] neg_hi:[0,1]
	v_pk_mul_f32 v[218:219], v[202:203], s[34:35] op_sel_hi:[0,1]
	v_pk_fma_f32 v[202:203], v[202:203], s[24:25], v[218:219] op_sel:[1,0,0]
	v_pk_add_f32 v[218:219], v[216:217], v[212:213]
	v_pk_add_f32 v[212:213], v[216:217], v[212:213] neg_lo:[0,1] neg_hi:[0,1]
	v_pk_add_f32 v[216:217], v[214:215], v[210:211]
	v_pk_add_f32 v[210:211], v[214:215], v[210:211] neg_lo:[0,1] neg_hi:[0,1]
	v_pk_add_f32 v[222:223], v[230:231], v[244:245] neg_lo:[0,1] neg_hi:[0,1]
	v_xor_b32_e32 v214, 0x80000000, v211
	v_mov_b32_e32 v215, v210
	v_pk_add_f32 v[210:211], v[218:219], v[216:217]
	v_pk_add_f32 v[220:221], v[212:213], v[214:215]
	v_pk_add_f32 v[216:217], v[218:219], v[216:217] neg_lo:[0,1] neg_hi:[0,1]
	v_pk_add_f32 v[212:213], v[212:213], v[214:215] neg_lo:[0,1] neg_hi:[0,1]
	v_pk_add_f32 v[214:215], v[242:243], v[224:225]
	v_pk_add_f32 v[218:219], v[242:243], v[224:225] neg_lo:[0,1] neg_hi:[0,1]
	v_pk_add_f32 v[224:225], v[226:227], v[248:249]
	v_pk_add_f32 v[226:227], v[226:227], v[248:249] neg_lo:[0,1] neg_hi:[0,1]
	s_nop 0
	v_xor_b32_e32 v242, 0x80000000, v227
	v_mov_b32_e32 v243, v226
	v_pk_add_f32 v[226:227], v[214:215], v[224:225]
	v_pk_add_f32 v[214:215], v[214:215], v[224:225] neg_lo:[0,1] neg_hi:[0,1]
	v_pk_add_f32 v[224:225], v[206:207], v[208:209]
	v_pk_add_f32 v[206:207], v[206:207], v[208:209] neg_lo:[0,1] neg_hi:[0,1]
	v_pk_add_f32 v[208:209], v[230:231], v[244:245]
	v_xor_b32_e32 v230, 0x80000000, v223
	v_mov_b32_e32 v231, v222
	v_pk_add_f32 v[222:223], v[224:225], v[208:209]
	v_pk_add_f32 v[208:209], v[224:225], v[208:209] neg_lo:[0,1] neg_hi:[0,1]
	v_pk_add_f32 v[224:225], v[246:247], v[202:203]
	v_pk_add_f32 v[202:203], v[246:247], v[202:203] neg_lo:[0,1] neg_hi:[0,1]
	v_pk_add_f32 v[248:249], v[218:219], v[242:243]
	v_xor_b32_e32 v228, 0x80000000, v203
	v_mov_b32_e32 v229, v202
	v_pk_add_f32 v[202:203], v[204:205], v[224:225]
	v_pk_add_f32 v[204:205], v[204:205], v[224:225] neg_lo:[0,1] neg_hi:[0,1]
	v_lshlrev_b32_e32 v225, 3, v181
	v_ashrrev_i32_e32 v181, 4, v181
	v_add_u32_e32 v224, s57, v238
	v_lshlrev_b32_e32 v181, 3, v181
	v_add3_u32 v181, v224, v225, v181
	v_pk_add_f32 v[218:219], v[218:219], v[242:243] neg_lo:[0,1] neg_hi:[0,1]
	v_pk_add_f32 v[242:243], v[206:207], v[230:231]
	v_pk_add_f32 v[206:207], v[206:207], v[230:231] neg_lo:[0,1] neg_hi:[0,1]
	v_pk_add_f32 v[230:231], v[200:201], v[228:229]
	v_pk_add_f32 v[200:201], v[200:201], v[228:229] neg_lo:[0,1] neg_hi:[0,1]
	ds_write2_b64 v181, v[210:211], v[226:227] offset1:17
	ds_write2_b64 v181, v[222:223], v[202:203] offset0:34 offset1:51
	ds_write2_b64 v181, v[220:221], v[248:249] offset0:68 offset1:85
	ds_write2_b64 v181, v[242:243], v[230:231] offset0:102 offset1:119
	ds_write2_b64 v181, v[216:217], v[214:215] offset0:136 offset1:153
	ds_write2_b64 v181, v[208:209], v[204:205] offset0:170 offset1:187
	ds_write2_b64 v181, v[212:213], v[218:219] offset0:204 offset1:221
	ds_write2_b64 v181, v[206:207], v[200:201] offset0:238 offset1:255

.LBB0_487:
	s_or_b64 exec, exec, s[2:3]
	v_mov_b32_e32 v0, v180
	s_waitcnt lgkmcnt(0)
	s_barrier
	s_nop 0
	v_cmp_gt_i32_e32 vcc, s16, v0
	s_and_saveexec_b64 s[2:3], vcc
	s_cbranch_execz .LBB0_489
	v_ashrrev_i32_e32 v1, 31, v0
	v_lshrrev_b32_e32 v1, 27, v1
	v_add_u32_e32 v1, v0, v1
	v_lshrrev_b32_e32 v2, 5, v1
	v_and_b32_e32 v1, 0xffffffe0, v1
	v_sub_u32_e32 v0, v0, v1
	v_lshrrev_b16_sdwa v1, v175, sext(v0) dst_sel:DWORD dst_unused:UNUSED_PAD src0_sel:DWORD src1_sel:BYTE_0
	v_and_b32_e32 v1, 15, v1
	v_add_u16_e32 v1, v0, v1
	v_ashrrev_i16_sdwa v8, v176, sext(v1) dst_sel:DWORD dst_unused:UNUSED_PAD src0_sel:DWORD src1_sel:BYTE_0
	v_and_b32_e32 v1, 0xf0, v1
	v_sub_u16_e32 v54, v0, v1
	v_mul_lo_u32 v91, v2, s17
	v_lshlrev_b32_e32 v2, 3, v0
	v_ashrrev_i32_e32 v0, 4, v0
	v_add_u32_e32 v1, s18, v91
	v_lshlrev_b32_e32 v0, 3, v0
	v_bfe_i32 v106, v54, 0, 8
	v_add3_u32 v4, v1, v2, v0
	v_mad_i32_i24 v107, v106, s19, 0
	ds_read2_b64 v[0:3], v4 offset1:34
	ds_read2_b64 v[58:61], v4 offset0:68 offset1:102
	ds_read2_b64 v[70:73], v4 offset0:136 offset1:170
	ds_read2_b64 v[74:77], v4 offset0:204 offset1:238
	v_add_u32_e32 v4, 0x800, v4
	v_add_u32_e32 v54, 0x808, v107
	ds_read2_b64 v[84:87], v4 offset0:16 offset1:50
	ds_read2_b64 v[108:111], v4 offset0:84 offset1:118
	ds_read2_b64 v[112:115], v4 offset0:152 offset1:186
	ds_read2_b64 v[4:7], v4 offset0:220 offset1:254
	ds_read2_b64 v[62:65], v54 offset1:1
	s_mov_b32 s31, s28
	s_mov_b32 s29, s14
	v_bfe_i32 v8, v8, 0, 16
	v_lshl_add_u32 v8, v8, 8, v106
	s_waitcnt lgkmcnt(0)
	v_pk_mul_f32 v[54:55], v[2:3], v[62:63] op_sel:[1,1] op_sel_hi:[1,0]
	s_nop 0
	v_pk_fma_f32 v[56:57], v[2:3], v[62:63], v[54:55] op_sel_hi:[0,1,1] neg_lo:[0,0,1]
	v_pk_mul_f32 v[2:3], v[58:59], v[64:65] op_sel:[1,1] op_sel_hi:[1,0]
	s_nop 0
	v_pk_fma_f32 v[54:55], v[58:59], v[64:65], v[2:3] op_sel_hi:[0,1,1] neg_lo:[0,0,1]
	v_add_u32_e32 v2, 0x818, v107
	ds_read2_b64 v[64:67], v2 offset1:1
	s_waitcnt lgkmcnt(0)
	v_pk_mul_f32 v[58:59], v[60:61], v[64:65] op_sel:[1,1] op_sel_hi:[1,0]
	s_nop 0
	v_pk_fma_f32 v[2:3], v[60:61], v[64:65], v[58:59] op_sel_hi:[0,1,1] neg_lo:[0,0,1]
	v_pk_mul_f32 v[58:59], v[70:71], v[66:67] op_sel:[1,1] op_sel_hi:[1,0]
	s_nop 0
	v_pk_fma_f32 v[64:65], v[70:71], v[66:67], v[58:59] op_sel_hi:[0,1,1] neg_lo:[0,0,1]
	v_add_u32_e32 v58, 0x828, v107
	ds_read2_b64 v[116:119], v58 offset1:1
	s_waitcnt lgkmcnt(0)
	v_pk_mul_f32 v[58:59], v[72:73], v[116:117] op_sel:[1,1] op_sel_hi:[1,0]
	s_nop 0
	v_pk_fma_f32 v[62:63], v[72:73], v[116:117], v[58:59] op_sel_hi:[0,1,1] neg_lo:[0,0,1]
	v_pk_mul_f32 v[58:59], v[74:75], v[118:119] op_sel:[1,1] op_sel_hi:[1,0]
	s_nop 0
	v_pk_fma_f32 v[60:61], v[74:75], v[118:119], v[58:59] op_sel_hi:[0,1,1] neg_lo:[0,0,1]
	v_add_u32_e32 v58, 0x838, v107
	ds_read2_b64 v[70:73], v58 offset1:1
	s_waitcnt lgkmcnt(0)
	v_pk_mul_f32 v[66:67], v[76:77], v[70:71] op_sel:[1,1] op_sel_hi:[1,0]
	s_nop 0
	v_pk_fma_f32 v[58:59], v[76:77], v[70:71], v[66:67] op_sel_hi:[0,1,1] neg_lo:[0,0,1]
	v_pk_mul_f32 v[66:67], v[84:85], v[72:73] op_sel:[1,1] op_sel_hi:[1,0]
	s_nop 0
	v_pk_fma_f32 v[74:75], v[84:85], v[72:73], v[66:67] op_sel_hi:[0,1,1] neg_lo:[0,0,1]
	v_add_u32_e32 v66, 0x848, v107
	ds_read2_b64 v[116:119], v66 offset1:1
	s_waitcnt lgkmcnt(0)
	v_pk_mul_f32 v[66:67], v[86:87], v[116:117] op_sel:[1,1] op_sel_hi:[1,0]
	s_nop 0
	v_pk_fma_f32 v[72:73], v[86:87], v[116:117], v[66:67] op_sel_hi:[0,1,1] neg_lo:[0,0,1]
	v_pk_mul_f32 v[66:67], v[108:109], v[118:119] op_sel:[1,1] op_sel_hi:[1,0]
	s_nop 0
	v_pk_fma_f32 v[70:71], v[108:109], v[118:119], v[66:67] op_sel_hi:[0,1,1] neg_lo:[0,0,1]
	v_add_u32_e32 v66, 0x858, v107
	ds_read2_b64 v[116:119], v66 offset1:1
	s_waitcnt lgkmcnt(0)
	v_pk_mul_f32 v[76:77], v[110:111], v[116:117] op_sel:[1,1] op_sel_hi:[1,0]
	s_nop 0
	v_pk_fma_f32 v[66:67], v[110:111], v[116:117], v[76:77] op_sel_hi:[0,1,1] neg_lo:[0,0,1]
	v_pk_mul_f32 v[76:77], v[112:113], v[118:119] op_sel:[1,1] op_sel_hi:[1,0]
	s_nop 0
	v_pk_fma_f32 v[86:87], v[112:113], v[118:119], v[76:77] op_sel_hi:[0,1,1] neg_lo:[0,0,1]
	v_add_u32_e32 v76, 0x868, v107
	ds_read2_b64 v[108:111], v76 offset1:1
	s_waitcnt lgkmcnt(0)
	v_pk_mul_f32 v[76:77], v[114:115], v[108:109] op_sel:[1,1] op_sel_hi:[1,0]
	s_nop 0
	v_pk_fma_f32 v[84:85], v[114:115], v[108:109], v[76:77] op_sel_hi:[0,1,1] neg_lo:[0,0,1]
	v_pk_mul_f32 v[108:109], v[4:5], v[110:111] op_sel:[1,1] op_sel_hi:[1,0]
	v_pk_fma_f32 v[76:77], v[4:5], v[110:111], v[108:109] op_sel_hi:[0,1,1] neg_lo:[0,0,1]
	ds_read_b64 v[4:5], v107 offset:2168
	s_waitcnt lgkmcnt(0)
	v_pk_mul_f32 v[108:109], v[6:7], v[4:5] op_sel:[1,1] op_sel_hi:[1,0]
	s_nop 0
	v_pk_fma_f32 v[110:111], v[6:7], v[4:5], v[108:109] op_sel_hi:[0,1,1] neg_lo:[0,0,1]
	v_pk_add_f32 v[4:5], v[0:1], v[74:75]
	v_pk_add_f32 v[6:7], v[64:65], v[86:87]
	v_pk_add_f32 v[64:65], v[64:65], v[86:87] neg_lo:[0,1] neg_hi:[0,1]
	v_pk_add_f32 v[0:1], v[0:1], v[74:75] neg_lo:[0,1] neg_hi:[0,1]
	v_xor_b32_e32 v75, 0x80000000, v64
	v_mov_b32_e32 v74, v65
	v_pk_add_f32 v[64:65], v[4:5], v[6:7]
	v_pk_add_f32 v[4:5], v[4:5], v[6:7] neg_lo:[0,1] neg_hi:[0,1]
	v_pk_add_f32 v[6:7], v[56:57], v[72:73]
	v_pk_add_f32 v[56:57], v[56:57], v[72:73] neg_lo:[0,1] neg_hi:[0,1]
	v_pk_add_f32 v[72:73], v[62:63], v[84:85]
	v_pk_add_f32 v[62:63], v[62:63], v[84:85] neg_lo:[0,1] neg_hi:[0,1]
	v_pk_add_f32 v[86:87], v[0:1], v[74:75]
	v_pk_add_f32 v[0:1], v[0:1], v[74:75] neg_lo:[0,1] neg_hi:[0,1]
	v_xor_b32_e32 v75, 0x80000000, v62
	v_mov_b32_e32 v74, v63
	v_pk_add_f32 v[62:63], v[6:7], v[72:73]
	v_pk_add_f32 v[6:7], v[6:7], v[72:73] neg_lo:[0,1] neg_hi:[0,1]
	v_pk_add_f32 v[72:73], v[54:55], v[70:71]
	v_pk_add_f32 v[54:55], v[54:55], v[70:71] neg_lo:[0,1] neg_hi:[0,1]
	v_pk_add_f32 v[70:71], v[60:61], v[76:77]
	v_pk_add_f32 v[60:61], v[60:61], v[76:77] neg_lo:[0,1] neg_hi:[0,1]
	v_pk_add_f32 v[84:85], v[56:57], v[74:75]
	v_pk_add_f32 v[56:57], v[56:57], v[74:75] neg_lo:[0,1] neg_hi:[0,1]
	v_xor_b32_e32 v75, 0x80000000, v60
	v_mov_b32_e32 v74, v61
	v_pk_add_f32 v[60:61], v[72:73], v[70:71]
	v_pk_add_f32 v[70:71], v[72:73], v[70:71] neg_lo:[0,1] neg_hi:[0,1]
	v_pk_add_f32 v[72:73], v[2:3], v[66:67]
	v_pk_add_f32 v[2:3], v[2:3], v[66:67] neg_lo:[0,1] neg_hi:[0,1]
	v_pk_add_f32 v[66:67], v[58:59], v[110:111]
	v_pk_add_f32 v[58:59], v[58:59], v[110:111] neg_lo:[0,1] neg_hi:[0,1]
	v_pk_add_f32 v[76:77], v[54:55], v[74:75]
	v_pk_add_f32 v[54:55], v[54:55], v[74:75] neg_lo:[0,1] neg_hi:[0,1]
	v_xor_b32_e32 v75, 0x80000000, v58
	v_mov_b32_e32 v74, v59
	v_pk_add_f32 v[58:59], v[72:73], v[66:67]
	v_pk_add_f32 v[66:67], v[72:73], v[66:67] neg_lo:[0,1] neg_hi:[0,1]
	v_pk_mul_f32 v[72:73], v[84:85], s[14:15] op_sel_hi:[1,0]
	v_pk_add_f32 v[108:109], v[2:3], v[74:75]
	v_pk_add_f32 v[2:3], v[2:3], v[74:75] neg_lo:[0,1] neg_hi:[0,1]
	v_pk_fma_f32 v[74:75], v[84:85], s[22:23], v[72:73] op_sel:[0,0,1] op_sel_hi:[1,0,0] neg_hi:[0,0,1]
	s_nop 0
	v_pk_mul_f32 v[72:73], v[6:7], s[24:25] op_sel_hi:[1,0]
	s_nop 0
	v_pk_fma_f32 v[84:85], v[6:7], s[24:25], v[72:73] op_sel:[0,0,1] op_sel_hi:[1,0,0] neg_hi:[0,0,1]
	v_pk_mul_f32 v[72:73], v[56:57], s[22:23] op_sel_hi:[1,0]
	v_pk_fma_f32 v[110:111], v[56:57], s[14:15], v[72:73] op_sel:[0,0,1] op_sel_hi:[1,0,0] neg_hi:[0,0,1]
	s_nop 0
	v_pk_mul_f32 v[56:57], v[76:77], s[24:25] op_sel_hi:[1,0]
	s_nop 0
	v_pk_fma_f32 v[72:73], v[76:77], s[24:25], v[56:57] op_sel:[0,0,1] op_sel_hi:[1,0,0] neg_hi:[0,0,1]
	s_nop 0
	v_pk_fma_f32 v[56:57], v[70:71], 0, v[70:71] op_sel:[0,0,1] op_sel_hi:[1,0,0] neg_hi:[0,0,1]
	s_nop 0
	v_pk_mul_f32 v[70:71], v[54:55], s[26:27] op_sel_hi:[1,0]
	s_nop 0
	v_pk_fma_f32 v[76:77], v[54:55], s[26:27], v[70:71] op_sel:[0,0,1] op_sel_hi:[1,0,0] neg_lo:[0,0,1]
	v_pk_mul_f32 v[70:71], v[108:109], s[22:23] op_sel_hi:[1,0]
	v_pk_fma_f32 v[112:113], v[108:109], s[14:15], v[70:71] op_sel:[0,0,1] op_sel_hi:[1,0,0] neg_hi:[0,0,1]
	v_pk_add_f32 v[54:55], v[0:1], v[76:77]
	v_pk_mul_f32 v[70:71], v[66:67], s[26:27] op_sel_hi:[1,0]
	v_pk_add_f32 v[0:1], v[0:1], v[76:77] neg_lo:[0,1] neg_hi:[0,1]
	v_pk_fma_f32 v[108:109], v[66:67], s[26:27], v[70:71] op_sel:[0,0,1] op_sel_hi:[1,0,0] neg_lo:[0,0,1]
	s_nop 0
	v_pk_mul_f32 v[66:67], v[2:3], s[30:31] op_sel:[1,0]
	v_pk_add_f32 v[6:7], v[84:85], v[108:109]
	v_pk_fma_f32 v[2:3], v[2:3], s[28:29], v[66:67] op_sel_hi:[0,1,1]
	v_pk_add_f32 v[66:67], v[64:65], v[60:61]
	v_pk_add_f32 v[60:61], v[64:65], v[60:61] neg_lo:[0,1] neg_hi:[0,1]
	v_pk_add_f32 v[64:65], v[62:63], v[58:59]
	v_pk_add_f32 v[58:59], v[62:63], v[58:59] neg_lo:[0,1] neg_hi:[0,1]
	s_nop 0
	v_xor_b32_e32 v63, 0x80000000, v58
	v_mov_b32_e32 v62, v59
	v_pk_add_f32 v[58:59], v[66:67], v[64:65]
	v_pk_add_f32 v[70:71], v[60:61], v[62:63]
	v_pk_add_f32 v[64:65], v[66:67], v[64:65] neg_lo:[0,1] neg_hi:[0,1]
	v_pk_add_f32 v[60:61], v[60:61], v[62:63] neg_lo:[0,1] neg_hi:[0,1]
	v_pk_add_f32 v[62:63], v[86:87], v[72:73]
	v_pk_add_f32 v[66:67], v[86:87], v[72:73] neg_lo:[0,1] neg_hi:[0,1]
	v_pk_add_f32 v[72:73], v[74:75], v[112:113]
	v_pk_add_f32 v[74:75], v[74:75], v[112:113] neg_lo:[0,1] neg_hi:[0,1]
	s_nop 0
	v_xor_b32_e32 v87, 0x80000000, v74
	v_mov_b32_e32 v86, v75
	v_pk_add_f32 v[74:75], v[62:63], v[72:73]
	v_pk_add_f32 v[62:63], v[62:63], v[72:73] neg_lo:[0,1] neg_hi:[0,1]
	v_pk_add_f32 v[72:73], v[4:5], v[56:57]
	v_pk_add_f32 v[4:5], v[4:5], v[56:57] neg_lo:[0,1] neg_hi:[0,1]
	v_pk_add_f32 v[56:57], v[84:85], v[108:109] neg_lo:[0,1] neg_hi:[0,1]
	v_pk_add_f32 v[112:113], v[66:67], v[86:87]
	v_xor_b32_e32 v85, 0x80000000, v56
	v_mov_b32_e32 v84, v57
	v_pk_add_f32 v[56:57], v[72:73], v[6:7]
	v_pk_add_f32 v[6:7], v[72:73], v[6:7] neg_lo:[0,1] neg_hi:[0,1]
	v_pk_add_f32 v[72:73], v[110:111], v[2:3]
	v_pk_add_f32 v[2:3], v[110:111], v[2:3] neg_lo:[0,1] neg_hi:[0,1]
	v_pk_add_f32 v[66:67], v[66:67], v[86:87] neg_lo:[0,1] neg_hi:[0,1]
	v_xor_b32_e32 v77, 0x80000000, v2
	v_mov_b32_e32 v76, v3
	v_pk_add_f32 v[2:3], v[54:55], v[72:73]
	v_pk_add_f32 v[54:55], v[54:55], v[72:73] neg_lo:[0,1] neg_hi:[0,1]
	v_lshlrev_b32_e32 v73, 3, v8
	v_ashrrev_i32_e32 v8, 4, v8
	v_add_u32_e32 v72, 0, v91
	v_lshlrev_b32_e32 v8, 3, v8
	v_add3_u32 v8, v72, v73, v8
	v_add_u32_e32 v72, 0x1800, v8
	v_pk_add_f32 v[86:87], v[4:5], v[84:85]
	v_pk_add_f32 v[4:5], v[4:5], v[84:85] neg_lo:[0,1] neg_hi:[0,1]
	v_pk_add_f32 v[84:85], v[0:1], v[76:77]
	v_pk_add_f32 v[0:1], v[0:1], v[76:77] neg_lo:[0,1] neg_hi:[0,1]
	ds_write2_b64 v72, v[58:59], v[74:75] offset0:16 offset1:33
	ds_write2_b64 v72, v[56:57], v[2:3] offset0:50 offset1:67
	ds_write2_b64 v72, v[70:71], v[112:113] offset0:84 offset1:101
	ds_write2_b64 v72, v[86:87], v[84:85] offset0:118 offset1:135
	ds_write2_b64 v72, v[64:65], v[62:63] offset0:152 offset1:169
	ds_write2_b64 v72, v[6:7], v[54:55] offset0:186 offset1:203
	ds_write2_b64 v72, v[60:61], v[66:67] offset0:220 offset1:237
	v_add_u32_e32 v2, 0x1c00, v8
	ds_write2_b64 v2, v[4:5], v[0:1] offset0:126 offset1:143
.LBB0_489:
	s_or_b64 exec, exec, s[2:3]
	v_ashrrev_i32_e32 v1, 2, v88
	v_add_u32_e32 v197, v18, v1
	s_waitcnt vmcnt(2)
	v_lshlrev_b32_e32 v1, 16, v52
	v_mul_f32_e32 v5, v94, v89
	v_and_b32_e32 v2, 0xffff0000, v52
	v_fmac_f32_e32 v5, v96, v1
	v_fmac_f32_e32 v5, v95, v2
	v_lshlrev_b32_e32 v3, 16, v53
	v_add_f32_e32 v89, v93, v5
	v_mul_f32_e32 v5, v96, v2
	v_fmac_f32_e32 v5, v94, v1
	v_mul_f32_e32 v1, v96, v3
	v_and_b32_e32 v4, 0xffff0000, v53
	v_fmac_f32_e32 v1, v94, v2
	v_fmac_f32_e32 v1, v95, v4
	v_add_f32_e32 v85, v93, v1
	v_mul_f32_e32 v1, v96, v4
	v_fmac_f32_e32 v1, v94, v3
	v_fmac_f32_e32 v5, v95, v3
	v_fmac_f32_e32 v1, v95, v105
	v_add_f32_e32 v91, v93, v5
	v_add_f32_e32 v87, v93, v1
	v_lshlrev_b32_e32 v1, 16, v50
	v_mul_f32_e32 v5, v94, v90
	v_and_b32_e32 v2, 0xffff0000, v50
	v_fmac_f32_e32 v5, v96, v1
	v_fmac_f32_e32 v5, v95, v2
	v_lshlrev_b32_e32 v3, 16, v51
	v_add_f32_e32 v88, v93, v5
	v_mul_f32_e32 v5, v96, v2
	v_fmac_f32_e32 v5, v94, v1
	v_mul_f32_e32 v1, v96, v3
	v_and_b32_e32 v4, 0xffff0000, v51
	v_fmac_f32_e32 v1, v94, v2
	v_fmac_f32_e32 v1, v95, v4
	v_add_f32_e32 v84, v93, v1
	v_mul_f32_e32 v1, v96, v4
	v_fmac_f32_e32 v1, v94, v3
	v_fmac_f32_e32 v1, v95, v104
	v_add_f32_e32 v86, v93, v1
	v_lshlrev_b32_e32 v1, 16, v48
	v_mul_f32_e32 v4, v101, v97
	v_and_b32_e32 v2, 0xffff0000, v48
	v_fmac_f32_e32 v4, v102, v1
	v_fmac_f32_e32 v4, v100, v2
	v_fmac_f32_e32 v5, v95, v3
	v_lshlrev_b32_e32 v8, 16, v49
	v_add_f32_e32 v95, v98, v4
	v_mul_f32_e32 v4, v102, v2
	v_fmac_f32_e32 v4, v101, v1
	v_mul_f32_e32 v1, v102, v8
	v_mov_b32_e32 v52, v180
	v_fmac_f32_e32 v1, v101, v2
	s_waitcnt lgkmcnt(0)
	s_barrier
	v_and_b32_e32 v3, 0xffff0000, v49
	v_ashrrev_i32_e32 v2, 31, v52
	v_add_u32_sdwa v2, v52, v2 dst_sel:DWORD dst_unused:UNUSED_PAD src0_sel:DWORD src1_sel:BYTE_3
	v_fmac_f32_e32 v1, v100, v3
	v_ashrrev_i32_e32 v2, 8, v2
	v_add_f32_e32 v90, v93, v5
	v_add_f32_e32 v93, v98, v1
	v_mul_f32_e32 v1, v102, v3
	v_mul_i32_i24_e32 v3, 0x100, v2
	v_sub_u32_e32 v3, v52, v3
	v_mul_i32_i24_e32 v48, 0x220, v2
	v_ashrrev_i32_e32 v2, 4, v3
	v_add_u32_e32 v49, 0x100, v3
	v_fmac_f32_e32 v4, v100, v8
	v_add_u32_e32 v2, v2, v3
	v_lshrrev_b32_e32 v50, 4, v49
	v_add_f32_e32 v97, v98, v4
	v_add_lshl_u32 v53, v2, v48, 3
	v_add3_u32 v4, v48, v3, v50
	v_add_u32_e32 v2, 0, v53
	v_lshl_add_u32 v4, v4, 3, 0
	v_lshl_add_u32 v6, v3, 3, 0
	ds_read_b64 v[2:3], v2 offset:6272
	ds_read_b64 v[4:5], v4 offset:8320
	ds_read_b64 v[6:7], v6 offset:4224
	v_fmac_f32_e32 v1, v101, v8
	v_fmac_f32_e32 v1, v100, v99
	v_add_f32_e32 v99, v98, v1
	v_add3_u32 v1, v48, v49, v50
	s_waitcnt lgkmcnt(0)
	v_pk_mul_f32 v[48:49], v[4:5], v[6:7] op_sel:[1,1] op_sel_hi:[1,0]
	v_lshl_add_u32 v1, v1, 3, s18
	v_pk_fma_f32 v[50:51], v[4:5], v[6:7], v[48:49] op_sel_hi:[0,1,1] neg_lo:[0,0,1]
	v_pk_add_f32 v[4:5], v[2:3], v[50:51]
	v_add_u32_e32 v6, s18, v53
	v_pk_add_f32 v[2:3], v[2:3], v[50:51] neg_lo:[0,1] neg_hi:[0,1]
	ds_write_b64 v6, v[4:5]
	ds_write_b64 v1, v[2:3]
	v_add_u32_e32 v1, 0x200, v52
	v_ashrrev_i32_e32 v2, 31, v1
	v_add_u32_sdwa v2, v1, v2 dst_sel:DWORD dst_unused:UNUSED_PAD src0_sel:DWORD src1_sel:BYTE_3
	v_ashrrev_i32_e32 v2, 8, v2
	v_mul_i32_i24_e32 v3, 0x100, v2
	v_sub_u32_e32 v1, v1, v3
	v_mul_i32_i24_e32 v8, 0x220, v2
	v_ashrrev_i32_e32 v2, 4, v1
	v_add_u32_e32 v48, 0x100, v1
	v_add_u32_e32 v2, v2, v1
	v_lshrrev_b32_e32 v49, 4, v48
	v_add_lshl_u32 v53, v2, v8, 3
	v_add3_u32 v3, v8, v1, v49
	v_add_u32_e32 v2, 0, v53
	v_lshl_add_u32 v4, v3, 3, 0
	v_lshl_add_u32 v1, v1, 3, 0
	ds_read_b64 v[2:3], v2 offset:6272
	ds_read_b64 v[4:5], v4 offset:8320
	ds_read_b64 v[6:7], v1 offset:4224
	v_add3_u32 v8, v8, v48, v49
	v_lshlrev_b32_e32 v1, 16, v46
	v_and_b32_e32 v54, 0xffff0000, v46
	v_lshlrev_b32_e32 v55, 16, v47
	s_waitcnt lgkmcnt(0)
	v_pk_mul_f32 v[48:49], v[4:5], v[6:7] op_sel:[1,1] op_sel_hi:[1,0]
	v_add_u32_e32 v0, 0x100, v18
	v_pk_fma_f32 v[50:51], v[4:5], v[6:7], v[48:49] op_sel_hi:[0,1,1] neg_lo:[0,0,1]
	v_pk_add_f32 v[4:5], v[2:3], v[50:51]
	v_add_u32_e32 v6, s18, v53
	ds_write_b64 v6, v[4:5]
	v_pk_add_f32 v[2:3], v[2:3], v[50:51] neg_lo:[0,1] neg_hi:[0,1]
	v_lshl_add_u32 v4, v8, 3, s18
	ds_write_b64 v4, v[2:3]
	v_add_u32_e32 v2, 0x400, v52
	v_ashrrev_i32_e32 v3, 31, v2
	v_add_u32_sdwa v3, v2, v3 dst_sel:DWORD dst_unused:UNUSED_PAD src0_sel:DWORD src1_sel:BYTE_3
	v_ashrrev_i32_e32 v3, 8, v3
	v_mul_i32_i24_e32 v4, 0x100, v3
	v_sub_u32_e32 v2, v2, v4
	v_mul_i32_i24_e32 v8, 0x220, v3
	v_ashrrev_i32_e32 v3, 4, v2
	v_add_u32_e32 v46, 0x100, v2
	v_add_u32_e32 v3, v3, v2
	v_lshrrev_b32_e32 v48, 4, v46
	v_add_lshl_u32 v50, v3, v8, 3
	v_add3_u32 v4, v8, v2, v48
	v_add_u32_e32 v3, 0, v50
	v_lshl_add_u32 v4, v4, 3, 0
	v_lshl_add_u32 v6, v2, 3, 0
	ds_read_b64 v[2:3], v3 offset:6272
	ds_read_b64 v[4:5], v4 offset:8320
	ds_read_b64 v[6:7], v6 offset:4224
	v_and_b32_e32 v51, 0xffff0000, v47
	v_add3_u32 v8, v8, v46, v48
	v_mul_f32_e32 v53, v101, v92
	v_fmac_f32_e32 v53, v102, v1
	s_waitcnt lgkmcnt(0)
	v_pk_mul_f32 v[46:47], v[4:5], v[6:7] op_sel:[1,1] op_sel_hi:[1,0]
	v_fmac_f32_e32 v53, v100, v54
	v_pk_fma_f32 v[48:49], v[4:5], v[6:7], v[46:47] op_sel_hi:[0,1,1] neg_lo:[0,0,1]
	v_pk_add_f32 v[4:5], v[2:3], v[48:49]
	v_add_u32_e32 v6, s18, v50
	ds_write_b64 v6, v[4:5]
	v_pk_add_f32 v[2:3], v[2:3], v[48:49] neg_lo:[0,1] neg_hi:[0,1]
	v_lshl_add_u32 v4, v8, 3, s18
	ds_write_b64 v4, v[2:3]
	v_add_u32_e32 v2, 0x600, v52
	v_ashrrev_i32_e32 v3, 31, v2
	v_add_u32_sdwa v3, v2, v3 dst_sel:DWORD dst_unused:UNUSED_PAD src0_sel:DWORD src1_sel:BYTE_3
	v_ashrrev_i32_e32 v3, 8, v3
	v_mul_i32_i24_e32 v4, 0x100, v3
	v_sub_u32_e32 v2, v2, v4
	v_mul_i32_i24_e32 v8, 0x220, v3
	v_ashrrev_i32_e32 v3, 4, v2
	v_add_u32_e32 v46, 0x100, v2
	v_add_u32_e32 v3, v3, v2
	v_lshrrev_b32_e32 v47, 4, v46
	v_add_lshl_u32 v50, v3, v8, 3
	v_add3_u32 v4, v8, v2, v47
	v_add_u32_e32 v3, 0, v50
	v_lshl_add_u32 v4, v4, 3, 0
	v_lshl_add_u32 v6, v2, 3, 0
	ds_read_b64 v[2:3], v3 offset:6272
	ds_read_b64 v[4:5], v4 offset:8320
	ds_read_b64 v[6:7], v6 offset:4224
	v_add3_u32 v8, v8, v46, v47
	v_add_f32_e32 v94, v98, v53
	v_mul_f32_e32 v53, v102, v54
	v_fmac_f32_e32 v53, v101, v1
	s_waitcnt lgkmcnt(0)
	v_pk_mul_f32 v[46:47], v[4:5], v[6:7] op_sel:[1,1] op_sel_hi:[1,0]
	v_fmac_f32_e32 v53, v100, v55
	v_pk_fma_f32 v[48:49], v[4:5], v[6:7], v[46:47] op_sel_hi:[0,1,1] neg_lo:[0,0,1]
	v_pk_add_f32 v[4:5], v[2:3], v[48:49]
	v_add_u32_e32 v6, s18, v50
	ds_write_b64 v6, v[4:5]
	v_pk_add_f32 v[2:3], v[2:3], v[48:49] neg_lo:[0,1] neg_hi:[0,1]
	v_lshl_add_u32 v4, v8, 3, s18
	ds_write_b64 v4, v[2:3]
	v_add_u32_e32 v2, 0x800, v52
	v_ashrrev_i32_e32 v3, 31, v2
	v_add_u32_sdwa v3, v2, v3 dst_sel:DWORD dst_unused:UNUSED_PAD src0_sel:DWORD src1_sel:BYTE_3
	v_ashrrev_i32_e32 v3, 8, v3
	v_mul_i32_i24_e32 v4, 0x100, v3
	v_sub_u32_e32 v2, v2, v4
	v_mul_i32_i24_e32 v8, 0x220, v3
	v_ashrrev_i32_e32 v3, 4, v2
	v_add_u32_e32 v46, 0x100, v2
	v_add_u32_e32 v3, v3, v2
	v_lshrrev_b32_e32 v47, 4, v46
	v_add_lshl_u32 v50, v3, v8, 3
	v_add3_u32 v4, v8, v2, v47
	v_add_u32_e32 v3, 0, v50
	v_lshl_add_u32 v4, v4, 3, 0
	v_lshl_add_u32 v6, v2, 3, 0
	ds_read_b64 v[2:3], v3 offset:6272
	ds_read_b64 v[4:5], v4 offset:8320
	ds_read_b64 v[6:7], v6 offset:4224
	v_add3_u32 v1, v8, v46, v47
	v_lshl_add_u32 v1, v1, 3, s18
	v_add_f32_e32 v96, v98, v53
	v_mul_lo_u32 v196, v132, s17
	s_waitcnt lgkmcnt(0)
	v_pk_mul_f32 v[46:47], v[4:5], v[6:7] op_sel:[1,1] op_sel_hi:[1,0]
	v_lshrrev_b32_e32 v0, 1, v0
	v_pk_fma_f32 v[48:49], v[4:5], v[6:7], v[46:47] op_sel_hi:[0,1,1] neg_lo:[0,0,1]
	v_pk_add_f32 v[4:5], v[2:3], v[48:49]
	v_add_u32_e32 v6, s18, v50
	v_pk_add_f32 v[2:3], v[2:3], v[48:49] neg_lo:[0,1] neg_hi:[0,1]
	ds_write_b64 v6, v[4:5]
	ds_write_b64 v1, v[2:3]
	v_add_u32_e32 v1, 0xa00, v52
	v_ashrrev_i32_e32 v2, 31, v1
	v_add_u32_sdwa v2, v1, v2 dst_sel:DWORD dst_unused:UNUSED_PAD src0_sel:DWORD src1_sel:BYTE_3
	v_ashrrev_i32_e32 v2, 8, v2
	v_mul_i32_i24_e32 v3, 0x100, v2
	v_sub_u32_e32 v1, v1, v3
	v_mul_i32_i24_e32 v8, 0x220, v2
	v_ashrrev_i32_e32 v2, 4, v1
	v_add_u32_e32 v46, 0x100, v1
	v_add_u32_e32 v2, v2, v1
	v_lshrrev_b32_e32 v47, 4, v46
	v_add_lshl_u32 v50, v2, v8, 3
	v_add3_u32 v3, v8, v1, v47
	v_add_u32_e32 v2, 0, v50
	v_lshl_add_u32 v4, v3, 3, 0
	v_lshl_add_u32 v1, v1, 3, 0
	ds_read_b64 v[2:3], v2 offset:6272
	ds_read_b64 v[4:5], v4 offset:8320
	ds_read_b64 v[6:7], v1 offset:4224
	v_add3_u32 v8, v8, v46, v47
	v_mul_f32_e32 v1, v102, v55
	v_fmac_f32_e32 v1, v101, v54
	v_fmac_f32_e32 v1, v100, v51
	s_waitcnt lgkmcnt(0)
	v_pk_mul_f32 v[46:47], v[4:5], v[6:7] op_sel:[1,1] op_sel_hi:[1,0]
	v_add_f32_e32 v92, v98, v1
	v_pk_fma_f32 v[48:49], v[4:5], v[6:7], v[46:47] op_sel_hi:[0,1,1] neg_lo:[0,0,1]
	v_pk_add_f32 v[4:5], v[2:3], v[48:49]
	v_add_u32_e32 v6, s18, v50
	ds_write_b64 v6, v[4:5]
	v_pk_add_f32 v[2:3], v[2:3], v[48:49] neg_lo:[0,1] neg_hi:[0,1]
	v_lshl_add_u32 v4, v8, 3, s18
	ds_write_b64 v4, v[2:3]
	v_add_u32_e32 v2, 0xc00, v52
	v_ashrrev_i32_e32 v3, 31, v2
	v_add_u32_sdwa v3, v2, v3 dst_sel:DWORD dst_unused:UNUSED_PAD src0_sel:DWORD src1_sel:BYTE_3
	v_ashrrev_i32_e32 v3, 8, v3
	v_mul_i32_i24_e32 v4, 0x100, v3
	v_sub_u32_e32 v2, v2, v4
	v_mul_i32_i24_e32 v8, 0x220, v3
	v_ashrrev_i32_e32 v3, 4, v2
	v_add_u32_e32 v46, 0x100, v2
	v_add_u32_e32 v3, v3, v2
	v_lshrrev_b32_e32 v47, 4, v46
	v_add_lshl_u32 v50, v3, v8, 3
	v_add3_u32 v4, v8, v2, v47
	v_add_u32_e32 v3, 0, v50
	v_lshl_add_u32 v4, v4, 3, 0
	v_lshl_add_u32 v6, v2, 3, 0
	ds_read_b64 v[2:3], v3 offset:6272
	ds_read_b64 v[4:5], v4 offset:8320
	ds_read_b64 v[6:7], v6 offset:4224
	v_add3_u32 v8, v8, v46, v47
	v_mul_f32_e32 v1, v102, v51
	v_fmac_f32_e32 v1, v101, v55
	v_fmac_f32_e32 v1, v100, v103
	s_waitcnt lgkmcnt(0)
	v_pk_mul_f32 v[46:47], v[4:5], v[6:7] op_sel:[1,1] op_sel_hi:[1,0]
	v_add_f32_e32 v98, v98, v1
	v_pk_fma_f32 v[48:49], v[4:5], v[6:7], v[46:47] op_sel_hi:[0,1,1] neg_lo:[0,0,1]
	v_pk_add_f32 v[4:5], v[2:3], v[48:49]
	v_add_u32_e32 v6, s18, v50
	ds_write_b64 v6, v[4:5]
	v_pk_add_f32 v[2:3], v[2:3], v[48:49] neg_lo:[0,1] neg_hi:[0,1]
	v_lshl_add_u32 v4, v8, 3, s18
	ds_write_b64 v4, v[2:3]
	v_add_u32_e32 v2, 0xe00, v52
	v_ashrrev_i32_e32 v3, 31, v2
	v_add_u32_sdwa v3, v2, v3 dst_sel:DWORD dst_unused:UNUSED_PAD src0_sel:DWORD src1_sel:BYTE_3
	v_ashrrev_i32_e32 v3, 8, v3
	v_mul_i32_i24_e32 v4, 0x100, v3
	v_sub_u32_e32 v2, v2, v4
	v_mul_i32_i24_e32 v8, 0x220, v3
	v_ashrrev_i32_e32 v3, 4, v2
	v_add_u32_e32 v46, 0x100, v2
	v_add_u32_e32 v3, v3, v2
	v_lshrrev_b32_e32 v47, 4, v46
	v_add_lshl_u32 v50, v3, v8, 3
	v_add3_u32 v4, v8, v2, v47
	v_add_u32_e32 v3, 0, v50
	v_lshl_add_u32 v4, v4, 3, 0
	v_lshl_add_u32 v6, v2, 3, 0
	ds_read_b64 v[2:3], v3 offset:6272
	ds_read_b64 v[4:5], v4 offset:8320
	ds_read_b64 v[6:7], v6 offset:4224
	v_add3_u32 v8, v8, v46, v47
	v_mov_b32_e32 v1, s18
	v_and_b32_e32 v0, 0x7ffffff8, v0
	s_waitcnt lgkmcnt(0)
	v_pk_mul_f32 v[46:47], v[4:5], v[6:7] op_sel:[1,1] op_sel_hi:[1,0]
	s_nop 0
	v_pk_fma_f32 v[48:49], v[4:5], v[6:7], v[46:47] op_sel_hi:[0,1,1] neg_lo:[0,0,1]
	v_pk_add_f32 v[4:5], v[2:3], v[48:49]
	v_add_u32_e32 v6, s18, v50
	ds_write_b64 v6, v[4:5]
	v_pk_add_f32 v[2:3], v[2:3], v[48:49] neg_lo:[0,1] neg_hi:[0,1]
	v_lshl_add_u32 v4, v8, 3, s18
	ds_write_b64 v4, v[2:3]
	v_lshrrev_b32_e32 v2, 27, v45
	v_add_u32_e32 v2, v44, v2
	v_and_b32_e32 v2, 0xffffffe0, v2
	v_lshrrev_b32_e32 v3, 5, v44
	v_sub_u32_e32 v2, v44, v2
	v_and_b32_e32 v3, 0xfffff8, v3
	v_mad_u32_u24 v1, v3, s17, v1
	v_ashrrev_i32_e32 v3, 4, v2
	v_add_u32_e32 v4, 32, v2
	v_add_u32_e32 v3, v3, v2
	v_lshrrev_b32_e32 v4, 4, v4
	v_lshl_add_u32 v3, v3, 3, v1
	v_add_u32_e32 v4, v4, v2
	s_waitcnt lgkmcnt(0)
	s_barrier
	v_lshl_add_u32 v4, v4, 3, v1
	ds_read_b64 v[100:101], v3
	ds_read_b64 v[44:45], v3 offset:4352
	ds_read_b64 v[102:103], v4 offset:256
	ds_read_b64 v[46:47], v4 offset:4608
	v_add_u32_e32 v3, 64, v2
	v_lshrrev_b32_e32 v3, 4, v3
	v_add_u32_e32 v4, 0x60, v2
	v_add_u32_e32 v3, v3, v2
	v_lshrrev_b32_e32 v4, 4, v4
	v_lshl_add_u32 v3, v3, 3, v1
	v_add_u32_e32 v4, v4, v2
	v_lshl_add_u32 v4, v4, 3, v1
	ds_read_b64 v[104:105], v3 offset:512
	ds_read_b64 v[48:49], v3 offset:4864
	ds_read_b64 v[106:107], v4 offset:768
	ds_read_b64 v[50:51], v4 offset:5120
	v_add_u32_e32 v3, 0x80, v2
	v_lshrrev_b32_e32 v3, 4, v3
	v_add_u32_e32 v4, 0xa0, v2
	v_add_u32_e32 v3, v3, v2
	v_lshrrev_b32_e32 v4, 4, v4
	v_lshl_add_u32 v3, v3, 3, v1
	v_add_u32_e32 v4, v4, v2
	v_lshl_add_u32 v4, v4, 3, v1
	ds_read_b64 v[108:109], v3 offset:1024
	ds_read_b64 v[52:53], v3 offset:5376
	ds_read_b64 v[110:111], v4 offset:1280
	ds_read_b64 v[54:55], v4 offset:5632
	v_add_u32_e32 v3, 0xc0, v2
	v_lshrrev_b32_e32 v3, 4, v3
	v_add_u32_e32 v4, 0xe0, v2
	v_add_u32_e32 v3, v3, v2
	v_lshrrev_b32_e32 v4, 4, v4
	v_lshl_add_u32 v3, v3, 3, v1
	v_add_u32_e32 v4, v4, v2
	v_lshl_add_u32 v4, v4, 3, v1
	ds_read_b64 v[112:113], v3 offset:1536
	ds_read_b64 v[56:57], v3 offset:5888
	ds_read_b64 v[114:115], v4 offset:1792
	ds_read_b64 v[58:59], v4 offset:6144
	v_add_u32_e32 v3, 0x100, v2
	v_lshrrev_b32_e32 v3, 4, v3
	v_add_u32_e32 v4, 0x120, v2
	v_add_u32_e32 v3, v3, v2
	v_lshrrev_b32_e32 v4, 4, v4
	v_lshl_add_u32 v3, v3, 3, v1
	v_add_u32_e32 v4, v4, v2
	v_lshl_add_u32 v4, v4, 3, v1
	ds_read_b64 v[116:117], v3 offset:2048
	ds_read_b64 v[60:61], v3 offset:6400
	ds_read_b64 v[118:119], v4 offset:2304
	ds_read_b64 v[62:63], v4 offset:6656
	v_add_u32_e32 v3, 0x140, v2
	v_lshrrev_b32_e32 v3, 4, v3
	v_add_u32_e32 v4, 0x160, v2
	v_add_u32_e32 v3, v3, v2
	v_lshrrev_b32_e32 v4, 4, v4
	v_lshl_add_u32 v3, v3, 3, v1
	v_add_u32_e32 v4, v4, v2
	v_lshl_add_u32 v4, v4, 3, v1
	ds_read_b64 v[120:121], v3 offset:2560
	ds_read_b64 v[64:65], v3 offset:6912
	ds_read_b64 v[122:123], v4 offset:2816
	ds_read_b64 v[66:67], v4 offset:7168
	v_add_u32_e32 v3, 0x180, v2
	v_lshrrev_b32_e32 v3, 4, v3
	v_add_u32_e32 v4, 0x1a0, v2
	v_add_u32_e32 v3, v3, v2
	v_lshrrev_b32_e32 v4, 4, v4
	v_lshl_add_u32 v3, v3, 3, v1
	v_add_u32_e32 v4, v4, v2
	v_lshl_add_u32 v4, v4, 3, v1
	ds_read_b64 v[124:125], v3 offset:3072
	ds_read_b64 v[70:71], v3 offset:7424
	ds_read_b64 v[126:127], v4 offset:3328
	ds_read_b64 v[72:73], v4 offset:7680
	v_add_u32_e32 v3, 0x1c0, v2
	v_lshrrev_b32_e32 v3, 4, v3
	v_add_u32_e32 v4, 0x1e0, v2
	v_add_u32_e32 v3, v3, v2
	v_lshrrev_b32_e32 v4, 4, v4
	v_lshl_add_u32 v3, v3, 3, v1
	v_add_u32_e32 v2, v4, v2
	v_lshl_add_u32 v1, v2, 3, v1
	ds_read_b64 v[128:129], v3 offset:3584
	ds_read_b64 v[74:75], v3 offset:7936
	ds_read_b64 v[130:131], v1 offset:3840
	ds_read_b64 v[76:77], v1 offset:8192
	v_add_u32_e32 v1, 0, v196
	v_lshlrev_b32_e32 v2, 3, v18
	v_lshl_add_u32 v8, v197, 3, v1
	v_add3_u32 v195, v1, v2, v0
	v_mov_b32_e32 v0, v180
	s_waitcnt lgkmcnt(0)
	s_barrier
	ds_write_b64 v8, v[94:95] offset:6272
	ds_write_b64 v195, v[202:203] offset:8320
	ds_write_b64 v8, v[96:97] offset:6280
	ds_write_b64 v195, v[202:203] offset:8328
	ds_write_b64 v8, v[92:93] offset:6288
	ds_write_b64 v195, v[202:203] offset:8336
	ds_write_b64 v8, v[98:99] offset:6296
	ds_write_b64 v195, v[202:203] offset:8344
	ds_write_b64 v8, v[88:89] offset:41088
	ds_write_b64 v195, v[202:203] offset:43136
	ds_write_b64 v8, v[90:91] offset:41096
	ds_write_b64 v195, v[202:203] offset:43144
	ds_write_b64 v8, v[84:85] offset:41104
	ds_write_b64 v195, v[202:203] offset:43152
	ds_write_b64 v8, v[86:87] offset:41112
	ds_write_b64 v195, v[202:203] offset:43160
	s_waitcnt lgkmcnt(0)
	s_barrier
	s_nop 0
	v_cmp_gt_i32_e32 vcc, s16, v0
	s_and_saveexec_b64 s[2:3], vcc
	s_cbranch_execz .LBB0_491
	v_ashrrev_i32_e32 v1, 31, v0
	v_lshrrev_b32_e32 v1, 27, v1
	v_add_u32_e32 v1, v0, v1
	v_lshrrev_b32_e32 v2, 5, v1
	v_and_b32_e32 v1, 0xffffffe0, v1
	v_sub_u32_e32 v181, v0, v1
	v_mul_lo_u32 v206, v2, s17
	v_ashrrev_i32_e32 v1, 4, v181
	v_add_u32_e32 v0, 0, v206
	v_lshlrev_b32_e32 v207, 3, v181
	v_lshlrev_b32_e32 v1, 3, v1
	v_add3_u32 v152, v0, v207, v1
	v_add_u32_e32 v136, 0x1800, v152
	v_add_u32_e32 v148, 0x2000, v152
	ds_read2_b64 v[0:3], v136 offset0:16 offset1:50
	ds_read2_b64 v[4:7], v136 offset0:84 offset1:118
	ds_read2_b64 v[132:135], v136 offset0:152 offset1:186
	ds_read2_b64 v[136:139], v136 offset0:220 offset1:254
	ds_read2_b64 v[140:143], v148 offset0:32 offset1:66
	ds_read2_b64 v[144:147], v148 offset0:100 offset1:134
	ds_read2_b64 v[148:151], v148 offset0:168 offset1:202
	v_add_u32_e32 v152, 0x2400, v152
	ds_read2_b64 v[152:155], v152 offset0:108 offset1:142
	s_waitcnt lgkmcnt(3)
	v_pk_add_f32 v[156:157], v[0:1], v[140:141]
	v_pk_add_f32 v[0:1], v[0:1], v[140:141] neg_lo:[0,1] neg_hi:[0,1]
	s_waitcnt lgkmcnt(1)
	v_pk_add_f32 v[140:141], v[132:133], v[148:149]
	v_pk_add_f32 v[132:133], v[132:133], v[148:149] neg_lo:[0,1] neg_hi:[0,1]
	s_mov_b32 s31, s28
	v_xor_b32_e32 v149, 0x80000000, v132
	v_mov_b32_e32 v148, v133
	v_pk_add_f32 v[198:199], v[0:1], v[148:149]
	v_pk_add_f32 v[0:1], v[0:1], v[148:149] neg_lo:[0,1] neg_hi:[0,1]
	v_pk_add_f32 v[148:149], v[2:3], v[142:143]
	v_pk_add_f32 v[2:3], v[2:3], v[142:143] neg_lo:[0,1] neg_hi:[0,1]
	v_pk_add_f32 v[142:143], v[134:135], v[150:151]
	v_pk_add_f32 v[134:135], v[134:135], v[150:151] neg_lo:[0,1] neg_hi:[0,1]
	v_pk_add_f32 v[132:133], v[156:157], v[140:141]
	v_xor_b32_e32 v151, 0x80000000, v134
	v_mov_b32_e32 v150, v135
	v_pk_add_f32 v[134:135], v[148:149], v[142:143]
	v_pk_add_f32 v[142:143], v[148:149], v[142:143] neg_lo:[0,1] neg_hi:[0,1]
	v_pk_add_f32 v[148:149], v[4:5], v[144:145]
	v_pk_add_f32 v[4:5], v[4:5], v[144:145] neg_lo:[0,1] neg_hi:[0,1]
	s_waitcnt lgkmcnt(0)
	v_pk_add_f32 v[144:145], v[136:137], v[152:153]
	v_pk_add_f32 v[136:137], v[136:137], v[152:153] neg_lo:[0,1] neg_hi:[0,1]
	v_pk_add_f32 v[140:141], v[156:157], v[140:141] neg_lo:[0,1] neg_hi:[0,1]
	v_pk_add_f32 v[156:157], v[2:3], v[150:151]
	v_pk_add_f32 v[2:3], v[2:3], v[150:151] neg_lo:[0,1] neg_hi:[0,1]
	v_xor_b32_e32 v151, 0x80000000, v136
	v_mov_b32_e32 v150, v137
	v_pk_add_f32 v[136:137], v[148:149], v[144:145]
	v_pk_add_f32 v[144:145], v[148:149], v[144:145] neg_lo:[0,1] neg_hi:[0,1]
	v_pk_add_f32 v[148:149], v[6:7], v[146:147]
	v_pk_add_f32 v[6:7], v[6:7], v[146:147] neg_lo:[0,1] neg_hi:[0,1]
	v_pk_add_f32 v[146:147], v[138:139], v[154:155]
	v_pk_add_f32 v[138:139], v[138:139], v[154:155] neg_lo:[0,1] neg_hi:[0,1]
	v_pk_add_f32 v[152:153], v[4:5], v[150:151]
	v_pk_add_f32 v[4:5], v[4:5], v[150:151] neg_lo:[0,1] neg_hi:[0,1]
	v_xor_b32_e32 v151, 0x80000000, v138
	v_mov_b32_e32 v150, v139
	v_pk_add_f32 v[138:139], v[148:149], v[146:147]
	v_pk_add_f32 v[146:147], v[148:149], v[146:147] neg_lo:[0,1] neg_hi:[0,1]
	v_pk_mul_f32 v[148:149], v[156:157], s[14:15] op_sel_hi:[1,0]
	v_pk_add_f32 v[154:155], v[6:7], v[150:151]
	v_pk_add_f32 v[6:7], v[6:7], v[150:151] neg_lo:[0,1] neg_hi:[0,1]
	v_pk_fma_f32 v[150:151], v[156:157], s[22:23], v[148:149] op_sel:[0,0,1] op_sel_hi:[1,0,0] neg_hi:[0,0,1]
	s_mov_b32 s29, s14
	v_pk_mul_f32 v[148:149], v[142:143], s[24:25] op_sel_hi:[1,0]
	s_nop 0
	v_pk_fma_f32 v[156:157], v[142:143], s[24:25], v[148:149] op_sel:[0,0,1] op_sel_hi:[1,0,0]
	v_pk_fma_f32 v[142:143], v[142:143], s[24:25], v[148:149] op_sel_hi:[1,0,0] neg_lo:[0,0,1] neg_hi:[0,0,1]
	v_pk_mul_f32 v[148:149], v[2:3], s[22:23] op_sel_hi:[1,0]
	v_mov_b32_e32 v157, v143
	v_pk_fma_f32 v[200:201], v[2:3], s[14:15], v[148:149] op_sel:[0,0,1] op_sel_hi:[1,0,0] neg_hi:[0,0,1]
	s_nop 0
	v_pk_mul_f32 v[2:3], v[152:153], s[24:25] op_sel_hi:[1,0]
	s_nop 0
	v_pk_fma_f32 v[148:149], v[152:153], s[24:25], v[2:3] op_sel:[0,0,1] op_sel_hi:[1,0,0] neg_hi:[0,0,1]
	s_nop 0
	v_pk_fma_f32 v[2:3], v[144:145], 0, v[144:145] op_sel:[0,0,1] op_sel_hi:[1,0,0] neg_hi:[0,0,1]
	s_nop 0
	v_pk_mul_f32 v[144:145], v[4:5], s[26:27] op_sel_hi:[1,0]
	s_nop 0
	v_pk_fma_f32 v[152:153], v[4:5], s[26:27], v[144:145] op_sel:[0,0,1] op_sel_hi:[1,0,0] neg_lo:[0,0,1] neg_hi:[0,0,1]
	v_pk_fma_f32 v[4:5], v[4:5], s[26:27], v[144:145] op_sel_hi:[1,0,0]
	v_pk_mul_f32 v[144:145], v[154:155], s[22:23] op_sel_hi:[1,0]
	v_mov_b32_e32 v153, v5
	v_pk_fma_f32 v[204:205], v[154:155], s[14:15], v[144:145] op_sel:[0,0,1] op_sel_hi:[1,0,0]
	v_pk_fma_f32 v[144:145], v[154:155], s[14:15], v[144:145] op_sel:[0,0,1] op_sel_hi:[1,0,0] neg_lo:[0,0,1] neg_hi:[0,0,1]
	v_pk_add_f32 v[4:5], v[0:1], v[152:153]
	v_mov_b32_e32 v205, v145
	v_pk_mul_f32 v[144:145], v[146:147], s[26:27] op_sel_hi:[1,0]
	v_pk_add_f32 v[0:1], v[0:1], v[152:153] neg_lo:[0,1] neg_hi:[0,1]
	v_pk_fma_f32 v[154:155], v[146:147], s[26:27], v[144:145] op_sel:[0,0,1] op_sel_hi:[1,0,0] neg_lo:[0,0,1] neg_hi:[0,0,1]
	v_pk_fma_f32 v[144:145], v[146:147], s[26:27], v[144:145] op_sel_hi:[1,0,0]
	s_nop 0
	v_mov_b32_e32 v155, v145
	v_pk_mul_f32 v[144:145], v[6:7], s[30:31] op_sel:[1,0]
	v_pk_add_f32 v[142:143], v[156:157], v[154:155] neg_lo:[0,1] neg_hi:[0,1]
	v_pk_fma_f32 v[6:7], v[6:7], s[28:29], v[144:145] op_sel_hi:[0,1,1]
	v_pk_add_f32 v[144:145], v[132:133], v[136:137]
	v_pk_add_f32 v[132:133], v[132:133], v[136:137] neg_lo:[0,1] neg_hi:[0,1]
	v_pk_add_f32 v[136:137], v[134:135], v[138:139]
	v_pk_add_f32 v[134:135], v[134:135], v[138:139] neg_lo:[0,1] neg_hi:[0,1]
	s_nop 0
	v_xor_b32_e32 v139, 0x80000000, v134
	v_mov_b32_e32 v138, v135
	v_pk_add_f32 v[134:135], v[144:145], v[136:137]
	v_pk_add_f32 v[146:147], v[132:133], v[138:139]
	v_pk_add_f32 v[136:137], v[144:145], v[136:137] neg_lo:[0,1] neg_hi:[0,1]
	v_pk_add_f32 v[132:133], v[132:133], v[138:139] neg_lo:[0,1] neg_hi:[0,1]
	v_pk_add_f32 v[138:139], v[198:199], v[148:149]
	v_pk_add_f32 v[144:145], v[198:199], v[148:149] neg_lo:[0,1] neg_hi:[0,1]
	v_pk_add_f32 v[148:149], v[150:151], v[204:205]
	v_pk_add_f32 v[150:151], v[150:151], v[204:205] neg_lo:[0,1] neg_hi:[0,1]
	s_nop 0
	v_xor_b32_e32 v199, 0x80000000, v150
	v_mov_b32_e32 v198, v151
	v_pk_add_f32 v[150:151], v[138:139], v[148:149]
	v_pk_add_f32 v[138:139], v[138:139], v[148:149] neg_lo:[0,1] neg_hi:[0,1]
	v_pk_add_f32 v[148:149], v[140:141], v[2:3]
	v_pk_add_f32 v[2:3], v[140:141], v[2:3] neg_lo:[0,1] neg_hi:[0,1]
	v_pk_add_f32 v[140:141], v[156:157], v[154:155]
	v_xor_b32_e32 v155, 0x80000000, v142
	v_mov_b32_e32 v154, v143
	v_pk_add_f32 v[142:143], v[148:149], v[140:141]
	v_pk_add_f32 v[140:141], v[148:149], v[140:141] neg_lo:[0,1] neg_hi:[0,1]
	v_pk_add_f32 v[148:149], v[200:201], v[6:7]
	v_pk_add_f32 v[6:7], v[200:201], v[6:7] neg_lo:[0,1] neg_hi:[0,1]
	v_pk_add_f32 v[204:205], v[144:145], v[198:199]
	v_xor_b32_e32 v153, 0x80000000, v6
	v_mov_b32_e32 v152, v7
	v_pk_add_f32 v[6:7], v[4:5], v[148:149]
	v_pk_add_f32 v[4:5], v[4:5], v[148:149] neg_lo:[0,1] neg_hi:[0,1]
	v_add_u32_e32 v148, s18, v206
	v_lshlrev_b32_e32 v149, 7, v181
	v_add3_u32 v148, v148, v149, v207
	v_pk_add_f32 v[144:145], v[144:145], v[198:199] neg_lo:[0,1] neg_hi:[0,1]
	v_pk_add_f32 v[156:157], v[2:3], v[154:155]
	v_pk_add_f32 v[2:3], v[2:3], v[154:155] neg_lo:[0,1] neg_hi:[0,1]
	v_pk_add_f32 v[154:155], v[0:1], v[152:153]
	v_pk_add_f32 v[0:1], v[0:1], v[152:153] neg_lo:[0,1] neg_hi:[0,1]
	ds_write2_b64 v148, v[134:135], v[150:151] offset1:1
	ds_write2_b64 v148, v[142:143], v[6:7] offset0:2 offset1:3
	ds_write2_b64 v148, v[146:147], v[204:205] offset0:4 offset1:5
	ds_write2_b64 v148, v[156:157], v[154:155] offset0:6 offset1:7
	ds_write2_b64 v148, v[136:137], v[138:139] offset0:8 offset1:9
	ds_write2_b64 v148, v[140:141], v[4:5] offset0:10 offset1:11
	ds_write2_b64 v148, v[132:133], v[144:145] offset0:12 offset1:13
	ds_write2_b64 v148, v[2:3], v[0:1] offset0:14 offset1:15
